# mixC: conv_unit loop de-serialised (hoisted weights, 4-deep row prefetch) + VTs staging loads batched
# speedup vs baseline: 1.0266x; 1.0266x over previous
; DI void conv_unit(const u16* __restrict__ PM, const float* __restrict__ conv_w, const float* __restrict__ conv_b, int b, int sl0, int ch, float scale, float* a8) {
;   { const float4 b0 = *(const float4*)(conv_b + ch), b1 = *(const float4*)(conv_b + ch + 4); a8[0] = b0.x; a8[1] = b0.y; a8[2] = b0.z; a8[3] = b0.w; a8[4] = b1.x; a8[5] = b1.y; a8[6] = b1.z; a8[7] = b1.w; }
; #pragma unroll
;   for (int j = 0; j < 4; ++j) {
;     const int sl = sl0 - 3 + j;
;     if (sl >= 0) {
;       const uint4 raw = *(const uint4*)(PM + ((size_t)b * SEQ + sl) * 1024 + ch);
;       float x8[8]; unpack8(raw, x8);
;       const float4 w0 = *(const float4*)(conv_w + j * 1024 + ch), w1 = *(const float4*)(conv_w + j * 1024 + ch + 4);
;       a8[0] += w0.x * x8[0]; a8[1] += w0.y * x8[1]; a8[2] += w0.z * x8[2]; a8[3] += w0.w * x8[3];
;       a8[4] += w1.x * x8[4]; a8[5] += w1.y * x8[5]; a8[6] += w1.z * x8[6]; a8[7] += w1.w * x8[7];
;     }
;   }
; DI void mlstmC_pair(const Params& p, char* lds_all, int pair) {
;     ...
;   for (int i = 0; i < 8; ++i) {
;     const int cg8 = ltid & 31, isK = cg8 >> 4, chl = (cg8 & 15) * 8, t = (ltid >> 5) + 8 * i;
;     float a8[8];
;     conv_unit(PM, p.in[5], p.in[6], b, c * 64 + t, (isK ? 512 : 0) + hd * 128 + chl, isK ? 0.08838834764831845f : 1.f, a8);
.LBB0_572:
	s_or_b64 exec, exec, s[0:1]
	v_ashrrev_i32_e32 v16, 9, v45
	v_bfe_u32 v44, v45, 7, 2
	v_lshlrev_b32_e32 v52, 3, v46
	v_and_b32_e32 v26, 16, v46
	v_lshlrev_b32_e32 v47, 7, v44
	v_and_b32_e32 v33, 0x78, v52
	v_lshlrev_b32_e32 v36, 5, v26
	v_ashrrev_i32_e32 v17, 31, v16
	v_or3_b32 v2, v47, v36, v33
	v_lshlrev_b64 v[34:35], 24, v[16:17]
	v_lshl_add_u64 v[0:1], s[40:41], 0, v[34:35]
	v_lshlrev_b32_e32 v20, 1, v2
	v_lshl_add_u64 v[18:19], v[0:1], 0, v[20:21]
	v_lshlrev_b32_e32 v20, 2, v2
	v_lshl_add_u64 v[22:23], s[62:63], 0, v[20:21]
	s_mov_b64 s[0:1], 0x3000
	v_lshl_add_u64 v[12:13], v[22:23], 0, s[0:1]
	s_movk_i32 s0, 0x3000
	v_add_co_u32_e64 v8, s[0:1], s0, v22
	global_load_dwordx4 v[0:3], v20, s[64:65] offset:16
	global_load_dwordx4 v[4:7], v20, s[64:65]
	v_addc_co_u32_e64 v9, s[0:1], 0, v23, s[0:1]
	global_load_dwordx4 v[8:11], v[8:9], off
	s_nop 0
	global_load_dwordx4 v[12:15], v[12:13], off offset:16
	s_mov_b32 s0, 0x11000
	v_mad_i32_i24 v51, v32, s0, 0
	v_add_u32_e32 v20, 0x4400, v51
	v_bfe_u32 v38, v46, 5, 3
	v_cmp_eq_u32_e64 s[0:1], 0, v26
	v_and_b32_e32 v40, 15, v46
	v_add_u32_e32 v32, s16, v32
	v_lshrrev_b32_e32 v37, 8, v46
	v_cndmask_b32_e64 v20, v20, v51, s[0:1]
	v_mul_u32_u24_e32 v39, 0x110, v38
	v_lshlrev_b32_e32 v40, 4, v40
	v_and_b32_e32 v32, 0x180, v32
	v_add3_u32 v54, v39, v40, v20
	v_add_u16_e32 v20, s26, v37
	v_or3_b32 v32, v36, v32, v33
	v_and_b32_e32 v20, 0x7f, v20
	v_lshl_or_b32 v34, v32, 1, v34
	v_lshlrev_b32_e32 v32, 11, v38
	v_cndmask_b32_e64 v26, v48, 1.0, s[0:1]
	s_mov_b64 s[0:1], 0x1000
	v_lshl_or_b32 v55, v20, 6, v38
	v_lshl_or_b32 v20, v20, 17, v32
	v_lshl_add_u64 v[28:29], v[22:23], 0, s[0:1]
	s_mov_b64 s[0:1], 0x2000
	v_lshl_add_u64 v[32:33], v[34:35], 0, v[20:21]
	v_and_b32_e32 v42, 0xff, v46
	s_mov_b32 s2, 0
	v_lshl_add_u64 v[30:31], v[22:23], 0, s[0:1]
	v_mov_b32_e32 v27, v26
	v_lshl_add_u64 v[32:33], s[76:77], 0, v[32:33]
	global_load_dwordx4 v[94:97], v[22:23], off
	global_load_dwordx4 v[98:101], v[22:23], off offset:16
	global_load_dwordx4 v[102:105], v[28:29], off
	global_load_dwordx4 v[106:109], v[28:29], off offset:16
	global_load_dwordx4 v[110:113], v[30:31], off
	global_load_dwordx4 v[114:117], v[30:31], off offset:16
	s_movk_i32 s2, 0x800
	v_mov_b32_e32 v184, v55
	v_add_u32_e32 v185, -1, v184
	v_mov_b32_e32 v118, 0
	v_mov_b32_e32 v119, 0
	v_mov_b32_e32 v120, 0
	v_mov_b32_e32 v121, 0
	v_mov_b32_e32 v122, 0
	v_mov_b32_e32 v123, 0
	v_mov_b32_e32 v124, 0
	v_mov_b32_e32 v125, 0
	v_mov_b32_e32 v126, 0
	v_mov_b32_e32 v127, 0
	v_mov_b32_e32 v128, 0
	v_mov_b32_e32 v129, 0
	v_mad_i64_i32 v[186:187], s[0:1], v185, s2, v[18:19]
	v_cmp_lt_u32_e64 s[0:1], 2, v184
	s_and_saveexec_b64 s[4:5], s[0:1]
	global_load_dwordx4 v[118:121], v[186:187], off offset:-4096
	s_or_b64 exec, exec, s[4:5]
	v_cmp_lt_u32_e64 s[0:1], 1, v184
	s_and_saveexec_b64 s[4:5], s[0:1]
	global_load_dwordx4 v[122:125], v[186:187], off offset:-2048
	s_or_b64 exec, exec, s[4:5]
	v_cmp_ne_u32_e64 s[0:1], 0, v184
	s_and_saveexec_b64 s[4:5], s[0:1]
	global_load_dwordx4 v[126:129], v[186:187], off
	s_or_b64 exec, exec, s[4:5]
	global_load_dwordx4 v[130:133], v[186:187], off offset:2048
	v_add_u32_e32 v184, 8, v55
	v_add_u32_e32 v185, -1, v184
	v_mov_b32_e32 v134, 0
	v_mov_b32_e32 v135, 0
	v_mov_b32_e32 v136, 0
	v_mov_b32_e32 v137, 0
	v_mov_b32_e32 v138, 0
	v_mov_b32_e32 v139, 0
	v_mov_b32_e32 v140, 0
	v_mov_b32_e32 v141, 0
	v_mov_b32_e32 v142, 0
	v_mov_b32_e32 v143, 0
	v_mov_b32_e32 v144, 0
	v_mov_b32_e32 v145, 0
	v_mad_i64_i32 v[186:187], s[0:1], v185, s2, v[18:19]
	v_cmp_lt_u32_e64 s[0:1], 2, v184
	s_and_saveexec_b64 s[4:5], s[0:1]
	global_load_dwordx4 v[134:137], v[186:187], off offset:-4096
	s_or_b64 exec, exec, s[4:5]
	v_cmp_lt_u32_e64 s[0:1], 1, v184
	s_and_saveexec_b64 s[4:5], s[0:1]
	global_load_dwordx4 v[138:141], v[186:187], off offset:-2048
	s_or_b64 exec, exec, s[4:5]
	v_cmp_ne_u32_e64 s[0:1], 0, v184
	s_and_saveexec_b64 s[4:5], s[0:1]
	global_load_dwordx4 v[142:145], v[186:187], off
	s_or_b64 exec, exec, s[4:5]
	global_load_dwordx4 v[146:149], v[186:187], off offset:2048
	v_add_u32_e32 v184, 16, v55
	v_add_u32_e32 v185, -1, v184
	v_mov_b32_e32 v150, 0
	v_mov_b32_e32 v151, 0
	v_mov_b32_e32 v152, 0
	v_mov_b32_e32 v153, 0
	v_mov_b32_e32 v154, 0
	v_mov_b32_e32 v155, 0
	v_mov_b32_e32 v156, 0
	v_mov_b32_e32 v157, 0
	v_mov_b32_e32 v158, 0
	v_mov_b32_e32 v159, 0
	v_mov_b32_e32 v160, 0
	v_mov_b32_e32 v161, 0
	v_mad_i64_i32 v[186:187], s[0:1], v185, s2, v[18:19]
	v_cmp_lt_u32_e64 s[0:1], 2, v184
	s_and_saveexec_b64 s[4:5], s[0:1]
	global_load_dwordx4 v[150:153], v[186:187], off offset:-4096
	s_or_b64 exec, exec, s[4:5]
	v_cmp_lt_u32_e64 s[0:1], 1, v184
	s_and_saveexec_b64 s[4:5], s[0:1]
	global_load_dwordx4 v[154:157], v[186:187], off offset:-2048
	s_or_b64 exec, exec, s[4:5]
	v_cmp_ne_u32_e64 s[0:1], 0, v184
	s_and_saveexec_b64 s[4:5], s[0:1]
	global_load_dwordx4 v[158:161], v[186:187], off
	s_or_b64 exec, exec, s[4:5]
	global_load_dwordx4 v[162:165], v[186:187], off offset:2048
	v_add_u32_e32 v184, 24, v55
	v_add_u32_e32 v185, -1, v184
	v_mov_b32_e32 v166, 0
	v_mov_b32_e32 v167, 0
	v_mov_b32_e32 v168, 0
	v_mov_b32_e32 v169, 0
	v_mov_b32_e32 v170, 0
	v_mov_b32_e32 v171, 0
	v_mov_b32_e32 v172, 0
	v_mov_b32_e32 v173, 0
	v_mov_b32_e32 v174, 0
	v_mov_b32_e32 v175, 0
	v_mov_b32_e32 v176, 0
	v_mov_b32_e32 v177, 0
	v_mad_i64_i32 v[186:187], s[0:1], v185, s2, v[18:19]
	v_cmp_lt_u32_e64 s[0:1], 2, v184
	s_and_saveexec_b64 s[4:5], s[0:1]
	global_load_dwordx4 v[166:169], v[186:187], off offset:-4096
	s_or_b64 exec, exec, s[4:5]
	v_cmp_lt_u32_e64 s[0:1], 1, v184
	s_and_saveexec_b64 s[4:5], s[0:1]
	global_load_dwordx4 v[170:173], v[186:187], off offset:-2048
	s_or_b64 exec, exec, s[4:5]
	v_cmp_ne_u32_e64 s[0:1], 0, v184
	s_and_saveexec_b64 s[4:5], s[0:1]
	global_load_dwordx4 v[174:177], v[186:187], off
	s_or_b64 exec, exec, s[4:5]
	global_load_dwordx4 v[178:181], v[186:187], off offset:2048
	s_waitcnt vmcnt(12)
; DI unsigned pack2(float a, float b) { const f32x2 v = {a, b}; return __builtin_bit_cast(unsigned, __builtin_convertvector(v, bf16v2)); }
; DI void conv_unit(const u16* __restrict__ PM, const float* __restrict__ conv_w, const float* __restrict__ conv_b, int b, int sl0, int ch, float scale, float* a8) {
;   { const float4 b0 = *(const float4*)(conv_b + ch), b1 = *(const float4*)(conv_b + ch + 4); a8[0] = b0.x; a8[1] = b0.y; a8[2] = b0.z; a8[3] = b0.w; a8[4] = b1.x; a8[5] = b1.y; a8[6] = b1.z; a8[7] = b1.w; }
; #pragma unroll
;   for (int j = 0; j < 4; ++j) {
;     const int sl = sl0 - 3 + j;
;     if (sl >= 0) {
;       const uint4 raw = *(const uint4*)(PM + ((size_t)b * SEQ + sl) * 1024 + ch);
;       float x8[8]; unpack8(raw, x8);
;       const float4 w0 = *(const float4*)(conv_w + j * 1024 + ch), w1 = *(const float4*)(conv_w + j * 1024 + ch + 4);
;       a8[0] += w0.x * x8[0]; a8[1] += w0.y * x8[1]; a8[2] += w0.z * x8[2]; a8[3] += w0.w * x8[3];
;       a8[4] += w1.x * x8[4]; a8[5] += w1.y * x8[5]; a8[6] += w1.z * x8[6]; a8[7] += w1.w * x8[7];
;     }
;   }
; #pragma unroll
;   for (int e = 0; e < 8; ++e) { const float v = a8[e]; a8[e] = scale * v * __builtin_amdgcn_rcpf(1.f + __expf(-v)); }
; }
; DI void mlstmC_pair(const Params& p, char* lds_all, int pair) {
;     ...
;     const int cg8 = ltid & 31, isK = cg8 >> 4, chl = (cg8 & 15) * 8, t = (ltid >> 5) + 8 * i;
;     float a8[8];
;     conv_unit(PM, p.in[5], p.in[6], b, c * 64 + t, (isK ? 512 : 0) + hd * 128 + chl, isK ? 0.08838834764831845f : 1.f, a8);
;     uint4 o; o.x = pack2(a8[0], a8[1]); o.y = pack2(a8[2], a8[3]); o.z = pack2(a8[4], a8[5]); o.w = pack2(a8[6], a8[7]);
;     *(uint4*)((isK ? Ks : Qs) + t * 136 + chl) = o;
	v_lshlrev_b32_e32 v188, 16, v118
	v_and_b32_e32 v189, 0xffff0000, v118
	v_lshlrev_b32_e32 v190, 16, v119
	v_and_b32_e32 v191, 0xffff0000, v119
	v_lshlrev_b32_e32 v192, 16, v120
	v_and_b32_e32 v193, 0xffff0000, v120
	v_lshlrev_b32_e32 v194, 16, v121
	v_and_b32_e32 v195, 0xffff0000, v121
	v_pk_fma_f32 v[204:205], v[94:95], v[188:189], v[4:5]
	v_pk_fma_f32 v[206:207], v[96:97], v[190:191], v[6:7]
	v_pk_fma_f32 v[208:209], v[98:99], v[192:193], v[0:1]
	v_pk_fma_f32 v[210:211], v[100:101], v[194:195], v[2:3]
	v_lshlrev_b32_e32 v188, 16, v122
	v_and_b32_e32 v189, 0xffff0000, v122
	v_lshlrev_b32_e32 v190, 16, v123
	v_and_b32_e32 v191, 0xffff0000, v123
	v_lshlrev_b32_e32 v192, 16, v124
	v_and_b32_e32 v193, 0xffff0000, v124
	v_lshlrev_b32_e32 v194, 16, v125
	v_and_b32_e32 v195, 0xffff0000, v125
	v_pk_fma_f32 v[204:205], v[102:103], v[188:189], v[204:205]
	v_pk_fma_f32 v[206:207], v[104:105], v[190:191], v[206:207]
	v_pk_fma_f32 v[208:209], v[106:107], v[192:193], v[208:209]
	v_pk_fma_f32 v[210:211], v[108:109], v[194:195], v[210:211]
	v_lshlrev_b32_e32 v188, 16, v126
	v_and_b32_e32 v189, 0xffff0000, v126
	v_lshlrev_b32_e32 v190, 16, v127
	v_and_b32_e32 v191, 0xffff0000, v127
	v_lshlrev_b32_e32 v192, 16, v128
	v_and_b32_e32 v193, 0xffff0000, v128
	v_lshlrev_b32_e32 v194, 16, v129
	v_and_b32_e32 v195, 0xffff0000, v129
	v_pk_fma_f32 v[204:205], v[110:111], v[188:189], v[204:205]
	v_pk_fma_f32 v[206:207], v[112:113], v[190:191], v[206:207]
	v_pk_fma_f32 v[208:209], v[114:115], v[192:193], v[208:209]
	v_pk_fma_f32 v[210:211], v[116:117], v[194:195], v[210:211]
	v_lshlrev_b32_e32 v188, 16, v130
	v_and_b32_e32 v189, 0xffff0000, v130
	v_lshlrev_b32_e32 v190, 16, v131
	v_and_b32_e32 v191, 0xffff0000, v131
	v_lshlrev_b32_e32 v192, 16, v132
	v_and_b32_e32 v193, 0xffff0000, v132
	v_lshlrev_b32_e32 v194, 16, v133
	v_and_b32_e32 v195, 0xffff0000, v133
	v_pk_fma_f32 v[204:205], v[8:9], v[188:189], v[204:205]
	v_pk_fma_f32 v[206:207], v[10:11], v[190:191], v[206:207]
	v_pk_fma_f32 v[208:209], v[12:13], v[192:193], v[208:209]
	v_pk_fma_f32 v[210:211], v[14:15], v[194:195], v[210:211]
	v_mul_f32_e32 v212, 0xbfb8aa3b, v204
	v_mul_f32_e32 v213, 0xbfb8aa3b, v205
	v_mul_f32_e32 v214, 0xbfb8aa3b, v206
	v_mul_f32_e32 v215, 0xbfb8aa3b, v207
	v_mul_f32_e32 v216, 0xbfb8aa3b, v208
	v_mul_f32_e32 v217, 0xbfb8aa3b, v209
	v_mul_f32_e32 v218, 0xbfb8aa3b, v210
	v_mul_f32_e32 v219, 0xbfb8aa3b, v211
	v_pk_mul_f32 v[188:189], v[26:27], v[204:205]
	v_pk_mul_f32 v[190:191], v[26:27], v[206:207]
	v_pk_mul_f32 v[192:193], v[26:27], v[208:209]
	v_pk_mul_f32 v[194:195], v[26:27], v[210:211]
	v_exp_f32_e32 v212, v212
	v_exp_f32_e32 v213, v213
	v_exp_f32_e32 v214, v214
	v_exp_f32_e32 v215, v215
	v_exp_f32_e32 v216, v216
	v_exp_f32_e32 v217, v217
	v_exp_f32_e32 v218, v218
	v_exp_f32_e32 v219, v219
	v_add_f32_e32 v212, 1.0, v212
	v_add_f32_e32 v213, 1.0, v213
	v_add_f32_e32 v214, 1.0, v214
	v_add_f32_e32 v215, 1.0, v215
	v_add_f32_e32 v216, 1.0, v216
	v_add_f32_e32 v217, 1.0, v217
	v_add_f32_e32 v218, 1.0, v218
	v_add_f32_e32 v219, 1.0, v219
	v_rcp_f32_e32 v212, v212
	v_rcp_f32_e32 v213, v213
	v_rcp_f32_e32 v214, v214
	v_rcp_f32_e32 v215, v215
	v_rcp_f32_e32 v216, v216
	v_rcp_f32_e32 v217, v217
	v_rcp_f32_e32 v218, v218
	v_rcp_f32_e32 v219, v219
	v_pk_mul_f32 v[188:189], v[188:189], v[212:213]
	v_pk_mul_f32 v[190:191], v[190:191], v[214:215]
	v_pk_mul_f32 v[192:193], v[192:193], v[216:217]
	v_pk_mul_f32 v[194:195], v[194:195], v[218:219]
	v_cvt_pk_bf16_f32 v196, v188, v189
	v_cvt_pk_bf16_f32 v197, v190, v191
	v_cvt_pk_bf16_f32 v198, v192, v193
	v_cvt_pk_bf16_f32 v199, v194, v195
	ds_write_b128 v54, v[196:199]
	v_add_u32_e32 v184, 32, v55
	v_add_u32_e32 v185, -1, v184
	v_mov_b32_e32 v118, 0
	v_mov_b32_e32 v119, 0
	v_mov_b32_e32 v120, 0
	v_mov_b32_e32 v121, 0
	v_mov_b32_e32 v122, 0
	v_mov_b32_e32 v123, 0
	v_mov_b32_e32 v124, 0
	v_mov_b32_e32 v125, 0
	v_mov_b32_e32 v126, 0
	v_mov_b32_e32 v127, 0
	v_mov_b32_e32 v128, 0
	v_mov_b32_e32 v129, 0
	v_mad_i64_i32 v[186:187], s[0:1], v185, s2, v[18:19]
	v_cmp_lt_u32_e64 s[0:1], 2, v184
	s_and_saveexec_b64 s[4:5], s[0:1]
	global_load_dwordx4 v[118:121], v[186:187], off offset:-4096
	s_or_b64 exec, exec, s[4:5]
	v_cmp_lt_u32_e64 s[0:1], 1, v184
	s_and_saveexec_b64 s[4:5], s[0:1]
	global_load_dwordx4 v[122:125], v[186:187], off offset:-2048
	s_or_b64 exec, exec, s[4:5]
	v_cmp_ne_u32_e64 s[0:1], 0, v184
	s_and_saveexec_b64 s[4:5], s[0:1]
	global_load_dwordx4 v[126:129], v[186:187], off
	s_or_b64 exec, exec, s[4:5]
	global_load_dwordx4 v[130:133], v[186:187], off offset:2048
	s_waitcnt vmcnt(12)
; DI unsigned pack2(float a, float b) { const f32x2 v = {a, b}; return __builtin_bit_cast(unsigned, __builtin_convertvector(v, bf16v2)); }
; DI void conv_unit(const u16* __restrict__ PM, const float* __restrict__ conv_w, const float* __restrict__ conv_b, int b, int sl0, int ch, float scale, float* a8) {
;   { const float4 b0 = *(const float4*)(conv_b + ch), b1 = *(const float4*)(conv_b + ch + 4); a8[0] = b0.x; a8[1] = b0.y; a8[2] = b0.z; a8[3] = b0.w; a8[4] = b1.x; a8[5] = b1.y; a8[6] = b1.z; a8[7] = b1.w; }
; #pragma unroll
;   for (int j = 0; j < 4; ++j) {
;     const int sl = sl0 - 3 + j;
;     if (sl >= 0) {
;       const uint4 raw = *(const uint4*)(PM + ((size_t)b * SEQ + sl) * 1024 + ch);
;       float x8[8]; unpack8(raw, x8);
;       const float4 w0 = *(const float4*)(conv_w + j * 1024 + ch), w1 = *(const float4*)(conv_w + j * 1024 + ch + 4);
;       a8[0] += w0.x * x8[0]; a8[1] += w0.y * x8[1]; a8[2] += w0.z * x8[2]; a8[3] += w0.w * x8[3];
;       a8[4] += w1.x * x8[4]; a8[5] += w1.y * x8[5]; a8[6] += w1.z * x8[6]; a8[7] += w1.w * x8[7];
;     }
;   }
; #pragma unroll
;   for (int e = 0; e < 8; ++e) { const float v = a8[e]; a8[e] = scale * v * __builtin_amdgcn_rcpf(1.f + __expf(-v)); }
; }
; DI void mlstmC_pair(const Params& p, char* lds_all, int pair) {
;     ...
;     const int cg8 = ltid & 31, isK = cg8 >> 4, chl = (cg8 & 15) * 8, t = (ltid >> 5) + 8 * i;
;     float a8[8];
;     conv_unit(PM, p.in[5], p.in[6], b, c * 64 + t, (isK ? 512 : 0) + hd * 128 + chl, isK ? 0.08838834764831845f : 1.f, a8);
;     uint4 o; o.x = pack2(a8[0], a8[1]); o.y = pack2(a8[2], a8[3]); o.z = pack2(a8[4], a8[5]); o.w = pack2(a8[6], a8[7]);
;     *(uint4*)((isK ? Ks : Qs) + t * 136 + chl) = o;
	v_lshlrev_b32_e32 v188, 16, v134
	v_and_b32_e32 v189, 0xffff0000, v134
	v_lshlrev_b32_e32 v190, 16, v135
	v_and_b32_e32 v191, 0xffff0000, v135
	v_lshlrev_b32_e32 v192, 16, v136
	v_and_b32_e32 v193, 0xffff0000, v136
	v_lshlrev_b32_e32 v194, 16, v137
	v_and_b32_e32 v195, 0xffff0000, v137
	v_pk_fma_f32 v[204:205], v[94:95], v[188:189], v[4:5]
	v_pk_fma_f32 v[206:207], v[96:97], v[190:191], v[6:7]
	v_pk_fma_f32 v[208:209], v[98:99], v[192:193], v[0:1]
	v_pk_fma_f32 v[210:211], v[100:101], v[194:195], v[2:3]
	v_lshlrev_b32_e32 v188, 16, v138
	v_and_b32_e32 v189, 0xffff0000, v138
	v_lshlrev_b32_e32 v190, 16, v139
	v_and_b32_e32 v191, 0xffff0000, v139
	v_lshlrev_b32_e32 v192, 16, v140
	v_and_b32_e32 v193, 0xffff0000, v140
	v_lshlrev_b32_e32 v194, 16, v141
	v_and_b32_e32 v195, 0xffff0000, v141
	v_pk_fma_f32 v[204:205], v[102:103], v[188:189], v[204:205]
	v_pk_fma_f32 v[206:207], v[104:105], v[190:191], v[206:207]
	v_pk_fma_f32 v[208:209], v[106:107], v[192:193], v[208:209]
	v_pk_fma_f32 v[210:211], v[108:109], v[194:195], v[210:211]
	v_lshlrev_b32_e32 v188, 16, v142
	v_and_b32_e32 v189, 0xffff0000, v142
	v_lshlrev_b32_e32 v190, 16, v143
	v_and_b32_e32 v191, 0xffff0000, v143
	v_lshlrev_b32_e32 v192, 16, v144
	v_and_b32_e32 v193, 0xffff0000, v144
	v_lshlrev_b32_e32 v194, 16, v145
	v_and_b32_e32 v195, 0xffff0000, v145
	v_pk_fma_f32 v[204:205], v[110:111], v[188:189], v[204:205]
	v_pk_fma_f32 v[206:207], v[112:113], v[190:191], v[206:207]
	v_pk_fma_f32 v[208:209], v[114:115], v[192:193], v[208:209]
	v_pk_fma_f32 v[210:211], v[116:117], v[194:195], v[210:211]
	v_lshlrev_b32_e32 v188, 16, v146
	v_and_b32_e32 v189, 0xffff0000, v146
	v_lshlrev_b32_e32 v190, 16, v147
	v_and_b32_e32 v191, 0xffff0000, v147
	v_lshlrev_b32_e32 v192, 16, v148
	v_and_b32_e32 v193, 0xffff0000, v148
	v_lshlrev_b32_e32 v194, 16, v149
	v_and_b32_e32 v195, 0xffff0000, v149
	v_pk_fma_f32 v[204:205], v[8:9], v[188:189], v[204:205]
	v_pk_fma_f32 v[206:207], v[10:11], v[190:191], v[206:207]
	v_pk_fma_f32 v[208:209], v[12:13], v[192:193], v[208:209]
	v_pk_fma_f32 v[210:211], v[14:15], v[194:195], v[210:211]
	v_mul_f32_e32 v212, 0xbfb8aa3b, v204
	v_mul_f32_e32 v213, 0xbfb8aa3b, v205
	v_mul_f32_e32 v214, 0xbfb8aa3b, v206
	v_mul_f32_e32 v215, 0xbfb8aa3b, v207
	v_mul_f32_e32 v216, 0xbfb8aa3b, v208
	v_mul_f32_e32 v217, 0xbfb8aa3b, v209
	v_mul_f32_e32 v218, 0xbfb8aa3b, v210
	v_mul_f32_e32 v219, 0xbfb8aa3b, v211
	v_pk_mul_f32 v[188:189], v[26:27], v[204:205]
	v_pk_mul_f32 v[190:191], v[26:27], v[206:207]
	v_pk_mul_f32 v[192:193], v[26:27], v[208:209]
	v_pk_mul_f32 v[194:195], v[26:27], v[210:211]
	v_exp_f32_e32 v212, v212
	v_exp_f32_e32 v213, v213
	v_exp_f32_e32 v214, v214
	v_exp_f32_e32 v215, v215
	v_exp_f32_e32 v216, v216
	v_exp_f32_e32 v217, v217
	v_exp_f32_e32 v218, v218
	v_exp_f32_e32 v219, v219
	v_add_f32_e32 v212, 1.0, v212
	v_add_f32_e32 v213, 1.0, v213
	v_add_f32_e32 v214, 1.0, v214
	v_add_f32_e32 v215, 1.0, v215
	v_add_f32_e32 v216, 1.0, v216
	v_add_f32_e32 v217, 1.0, v217
	v_add_f32_e32 v218, 1.0, v218
	v_add_f32_e32 v219, 1.0, v219
	v_rcp_f32_e32 v212, v212
	v_rcp_f32_e32 v213, v213
	v_rcp_f32_e32 v214, v214
	v_rcp_f32_e32 v215, v215
	v_rcp_f32_e32 v216, v216
	v_rcp_f32_e32 v217, v217
	v_rcp_f32_e32 v218, v218
	v_rcp_f32_e32 v219, v219
	v_pk_mul_f32 v[188:189], v[188:189], v[212:213]
	v_pk_mul_f32 v[190:191], v[190:191], v[214:215]
	v_pk_mul_f32 v[192:193], v[192:193], v[216:217]
	v_pk_mul_f32 v[194:195], v[194:195], v[218:219]
	v_cvt_pk_bf16_f32 v196, v188, v189
	v_cvt_pk_bf16_f32 v197, v190, v191
	v_cvt_pk_bf16_f32 v198, v192, v193
	v_cvt_pk_bf16_f32 v199, v194, v195
	ds_write_b128 v54, v[196:199] offset:2176
	v_add_u32_e32 v184, 40, v55
	v_add_u32_e32 v185, -1, v184
	v_mov_b32_e32 v134, 0
	v_mov_b32_e32 v135, 0
	v_mov_b32_e32 v136, 0
	v_mov_b32_e32 v137, 0
	v_mov_b32_e32 v138, 0
	v_mov_b32_e32 v139, 0
	v_mov_b32_e32 v140, 0
	v_mov_b32_e32 v141, 0
	v_mov_b32_e32 v142, 0
	v_mov_b32_e32 v143, 0
	v_mov_b32_e32 v144, 0
	v_mov_b32_e32 v145, 0
	v_mad_i64_i32 v[186:187], s[0:1], v185, s2, v[18:19]
	v_cmp_lt_u32_e64 s[0:1], 2, v184
	s_and_saveexec_b64 s[4:5], s[0:1]
	global_load_dwordx4 v[134:137], v[186:187], off offset:-4096
	s_or_b64 exec, exec, s[4:5]
	v_cmp_lt_u32_e64 s[0:1], 1, v184
	s_and_saveexec_b64 s[4:5], s[0:1]
	global_load_dwordx4 v[138:141], v[186:187], off offset:-2048
	s_or_b64 exec, exec, s[4:5]
	v_cmp_ne_u32_e64 s[0:1], 0, v184
	s_and_saveexec_b64 s[4:5], s[0:1]
	global_load_dwordx4 v[142:145], v[186:187], off
	s_or_b64 exec, exec, s[4:5]
	global_load_dwordx4 v[146:149], v[186:187], off offset:2048
	s_waitcnt vmcnt(12)
; DI unsigned pack2(float a, float b) { const f32x2 v = {a, b}; return __builtin_bit_cast(unsigned, __builtin_convertvector(v, bf16v2)); }
; DI void conv_unit(const u16* __restrict__ PM, const float* __restrict__ conv_w, const float* __restrict__ conv_b, int b, int sl0, int ch, float scale, float* a8) {
;   { const float4 b0 = *(const float4*)(conv_b + ch), b1 = *(const float4*)(conv_b + ch + 4); a8[0] = b0.x; a8[1] = b0.y; a8[2] = b0.z; a8[3] = b0.w; a8[4] = b1.x; a8[5] = b1.y; a8[6] = b1.z; a8[7] = b1.w; }
; #pragma unroll
;   for (int j = 0; j < 4; ++j) {
;     const int sl = sl0 - 3 + j;
;     if (sl >= 0) {
;       const uint4 raw = *(const uint4*)(PM + ((size_t)b * SEQ + sl) * 1024 + ch);
;       float x8[8]; unpack8(raw, x8);
;       const float4 w0 = *(const float4*)(conv_w + j * 1024 + ch), w1 = *(const float4*)(conv_w + j * 1024 + ch + 4);
;       a8[0] += w0.x * x8[0]; a8[1] += w0.y * x8[1]; a8[2] += w0.z * x8[2]; a8[3] += w0.w * x8[3];
;       a8[4] += w1.x * x8[4]; a8[5] += w1.y * x8[5]; a8[6] += w1.z * x8[6]; a8[7] += w1.w * x8[7];
;     }
;   }
; #pragma unroll
;   for (int e = 0; e < 8; ++e) { const float v = a8[e]; a8[e] = scale * v * __builtin_amdgcn_rcpf(1.f + __expf(-v)); }
; }
; DI void mlstmC_pair(const Params& p, char* lds_all, int pair) {
;     ...
;     const int cg8 = ltid & 31, isK = cg8 >> 4, chl = (cg8 & 15) * 8, t = (ltid >> 5) + 8 * i;
;     float a8[8];
;     conv_unit(PM, p.in[5], p.in[6], b, c * 64 + t, (isK ? 512 : 0) + hd * 128 + chl, isK ? 0.08838834764831845f : 1.f, a8);
;     uint4 o; o.x = pack2(a8[0], a8[1]); o.y = pack2(a8[2], a8[3]); o.z = pack2(a8[4], a8[5]); o.w = pack2(a8[6], a8[7]);
;     *(uint4*)((isK ? Ks : Qs) + t * 136 + chl) = o;
	v_lshlrev_b32_e32 v188, 16, v150
	v_and_b32_e32 v189, 0xffff0000, v150
	v_lshlrev_b32_e32 v190, 16, v151
	v_and_b32_e32 v191, 0xffff0000, v151
	v_lshlrev_b32_e32 v192, 16, v152
	v_and_b32_e32 v193, 0xffff0000, v152
	v_lshlrev_b32_e32 v194, 16, v153
	v_and_b32_e32 v195, 0xffff0000, v153
	v_pk_fma_f32 v[204:205], v[94:95], v[188:189], v[4:5]
	v_pk_fma_f32 v[206:207], v[96:97], v[190:191], v[6:7]
	v_pk_fma_f32 v[208:209], v[98:99], v[192:193], v[0:1]
	v_pk_fma_f32 v[210:211], v[100:101], v[194:195], v[2:3]
	v_lshlrev_b32_e32 v188, 16, v154
	v_and_b32_e32 v189, 0xffff0000, v154
	v_lshlrev_b32_e32 v190, 16, v155
	v_and_b32_e32 v191, 0xffff0000, v155
	v_lshlrev_b32_e32 v192, 16, v156
	v_and_b32_e32 v193, 0xffff0000, v156
	v_lshlrev_b32_e32 v194, 16, v157
	v_and_b32_e32 v195, 0xffff0000, v157
	v_pk_fma_f32 v[204:205], v[102:103], v[188:189], v[204:205]
	v_pk_fma_f32 v[206:207], v[104:105], v[190:191], v[206:207]
	v_pk_fma_f32 v[208:209], v[106:107], v[192:193], v[208:209]
	v_pk_fma_f32 v[210:211], v[108:109], v[194:195], v[210:211]
	v_lshlrev_b32_e32 v188, 16, v158
	v_and_b32_e32 v189, 0xffff0000, v158
	v_lshlrev_b32_e32 v190, 16, v159
	v_and_b32_e32 v191, 0xffff0000, v159
	v_lshlrev_b32_e32 v192, 16, v160
	v_and_b32_e32 v193, 0xffff0000, v160
	v_lshlrev_b32_e32 v194, 16, v161
	v_and_b32_e32 v195, 0xffff0000, v161
	v_pk_fma_f32 v[204:205], v[110:111], v[188:189], v[204:205]
	v_pk_fma_f32 v[206:207], v[112:113], v[190:191], v[206:207]
	v_pk_fma_f32 v[208:209], v[114:115], v[192:193], v[208:209]
	v_pk_fma_f32 v[210:211], v[116:117], v[194:195], v[210:211]
	v_lshlrev_b32_e32 v188, 16, v162
	v_and_b32_e32 v189, 0xffff0000, v162
	v_lshlrev_b32_e32 v190, 16, v163
	v_and_b32_e32 v191, 0xffff0000, v163
	v_lshlrev_b32_e32 v192, 16, v164
	v_and_b32_e32 v193, 0xffff0000, v164
	v_lshlrev_b32_e32 v194, 16, v165
	v_and_b32_e32 v195, 0xffff0000, v165
	v_pk_fma_f32 v[204:205], v[8:9], v[188:189], v[204:205]
	v_pk_fma_f32 v[206:207], v[10:11], v[190:191], v[206:207]
	v_pk_fma_f32 v[208:209], v[12:13], v[192:193], v[208:209]
	v_pk_fma_f32 v[210:211], v[14:15], v[194:195], v[210:211]
	v_mul_f32_e32 v212, 0xbfb8aa3b, v204
	v_mul_f32_e32 v213, 0xbfb8aa3b, v205
	v_mul_f32_e32 v214, 0xbfb8aa3b, v206
	v_mul_f32_e32 v215, 0xbfb8aa3b, v207
	v_mul_f32_e32 v216, 0xbfb8aa3b, v208
	v_mul_f32_e32 v217, 0xbfb8aa3b, v209
	v_mul_f32_e32 v218, 0xbfb8aa3b, v210
	v_mul_f32_e32 v219, 0xbfb8aa3b, v211
	v_pk_mul_f32 v[188:189], v[26:27], v[204:205]
	v_pk_mul_f32 v[190:191], v[26:27], v[206:207]
	v_pk_mul_f32 v[192:193], v[26:27], v[208:209]
	v_pk_mul_f32 v[194:195], v[26:27], v[210:211]
	v_exp_f32_e32 v212, v212
	v_exp_f32_e32 v213, v213
	v_exp_f32_e32 v214, v214
	v_exp_f32_e32 v215, v215
	v_exp_f32_e32 v216, v216
	v_exp_f32_e32 v217, v217
	v_exp_f32_e32 v218, v218
	v_exp_f32_e32 v219, v219
	v_add_f32_e32 v212, 1.0, v212
	v_add_f32_e32 v213, 1.0, v213
	v_add_f32_e32 v214, 1.0, v214
	v_add_f32_e32 v215, 1.0, v215
	v_add_f32_e32 v216, 1.0, v216
	v_add_f32_e32 v217, 1.0, v217
	v_add_f32_e32 v218, 1.0, v218
	v_add_f32_e32 v219, 1.0, v219
	v_rcp_f32_e32 v212, v212
	v_rcp_f32_e32 v213, v213
	v_rcp_f32_e32 v214, v214
	v_rcp_f32_e32 v215, v215
	v_rcp_f32_e32 v216, v216
	v_rcp_f32_e32 v217, v217
	v_rcp_f32_e32 v218, v218
	v_rcp_f32_e32 v219, v219
	v_pk_mul_f32 v[188:189], v[188:189], v[212:213]
	v_pk_mul_f32 v[190:191], v[190:191], v[214:215]
	v_pk_mul_f32 v[192:193], v[192:193], v[216:217]
	v_pk_mul_f32 v[194:195], v[194:195], v[218:219]
	v_cvt_pk_bf16_f32 v196, v188, v189
	v_cvt_pk_bf16_f32 v197, v190, v191
	v_cvt_pk_bf16_f32 v198, v192, v193
	v_cvt_pk_bf16_f32 v199, v194, v195
	ds_write_b128 v54, v[196:199] offset:4352
	v_add_u32_e32 v184, 48, v55
	v_add_u32_e32 v185, -1, v184
	v_mov_b32_e32 v150, 0
	v_mov_b32_e32 v151, 0
	v_mov_b32_e32 v152, 0
	v_mov_b32_e32 v153, 0
	v_mov_b32_e32 v154, 0
	v_mov_b32_e32 v155, 0
	v_mov_b32_e32 v156, 0
	v_mov_b32_e32 v157, 0
	v_mov_b32_e32 v158, 0
	v_mov_b32_e32 v159, 0
	v_mov_b32_e32 v160, 0
	v_mov_b32_e32 v161, 0
	v_mad_i64_i32 v[186:187], s[0:1], v185, s2, v[18:19]
	v_cmp_lt_u32_e64 s[0:1], 2, v184
	s_and_saveexec_b64 s[4:5], s[0:1]
	global_load_dwordx4 v[150:153], v[186:187], off offset:-4096
	s_or_b64 exec, exec, s[4:5]
	v_cmp_lt_u32_e64 s[0:1], 1, v184
	s_and_saveexec_b64 s[4:5], s[0:1]
	global_load_dwordx4 v[154:157], v[186:187], off offset:-2048
	s_or_b64 exec, exec, s[4:5]
	v_cmp_ne_u32_e64 s[0:1], 0, v184
	s_and_saveexec_b64 s[4:5], s[0:1]
	global_load_dwordx4 v[158:161], v[186:187], off
	s_or_b64 exec, exec, s[4:5]
	global_load_dwordx4 v[162:165], v[186:187], off offset:2048
	s_waitcnt vmcnt(12)
; DI unsigned pack2(float a, float b) { const f32x2 v = {a, b}; return __builtin_bit_cast(unsigned, __builtin_convertvector(v, bf16v2)); }
; DI void conv_unit(const u16* __restrict__ PM, const float* __restrict__ conv_w, const float* __restrict__ conv_b, int b, int sl0, int ch, float scale, float* a8) {
;   { const float4 b0 = *(const float4*)(conv_b + ch), b1 = *(const float4*)(conv_b + ch + 4); a8[0] = b0.x; a8[1] = b0.y; a8[2] = b0.z; a8[3] = b0.w; a8[4] = b1.x; a8[5] = b1.y; a8[6] = b1.z; a8[7] = b1.w; }
; #pragma unroll
;   for (int j = 0; j < 4; ++j) {
;     const int sl = sl0 - 3 + j;
;     if (sl >= 0) {
;       const uint4 raw = *(const uint4*)(PM + ((size_t)b * SEQ + sl) * 1024 + ch);
;       float x8[8]; unpack8(raw, x8);
;       const float4 w0 = *(const float4*)(conv_w + j * 1024 + ch), w1 = *(const float4*)(conv_w + j * 1024 + ch + 4);
;       a8[0] += w0.x * x8[0]; a8[1] += w0.y * x8[1]; a8[2] += w0.z * x8[2]; a8[3] += w0.w * x8[3];
;       a8[4] += w1.x * x8[4]; a8[5] += w1.y * x8[5]; a8[6] += w1.z * x8[6]; a8[7] += w1.w * x8[7];
;     }
;   }
; #pragma unroll
;   for (int e = 0; e < 8; ++e) { const float v = a8[e]; a8[e] = scale * v * __builtin_amdgcn_rcpf(1.f + __expf(-v)); }
; }
; DI void mlstmC_pair(const Params& p, char* lds_all, int pair) {
;     ...
;     const int cg8 = ltid & 31, isK = cg8 >> 4, chl = (cg8 & 15) * 8, t = (ltid >> 5) + 8 * i;
;     float a8[8];
;     conv_unit(PM, p.in[5], p.in[6], b, c * 64 + t, (isK ? 512 : 0) + hd * 128 + chl, isK ? 0.08838834764831845f : 1.f, a8);
;     uint4 o; o.x = pack2(a8[0], a8[1]); o.y = pack2(a8[2], a8[3]); o.z = pack2(a8[4], a8[5]); o.w = pack2(a8[6], a8[7]);
;     *(uint4*)((isK ? Ks : Qs) + t * 136 + chl) = o;
	v_lshlrev_b32_e32 v188, 16, v166
	v_and_b32_e32 v189, 0xffff0000, v166
	v_lshlrev_b32_e32 v190, 16, v167
	v_and_b32_e32 v191, 0xffff0000, v167
	v_lshlrev_b32_e32 v192, 16, v168
	v_and_b32_e32 v193, 0xffff0000, v168
	v_lshlrev_b32_e32 v194, 16, v169
	v_and_b32_e32 v195, 0xffff0000, v169
	v_pk_fma_f32 v[204:205], v[94:95], v[188:189], v[4:5]
	v_pk_fma_f32 v[206:207], v[96:97], v[190:191], v[6:7]
	v_pk_fma_f32 v[208:209], v[98:99], v[192:193], v[0:1]
	v_pk_fma_f32 v[210:211], v[100:101], v[194:195], v[2:3]
	v_lshlrev_b32_e32 v188, 16, v170
	v_and_b32_e32 v189, 0xffff0000, v170
	v_lshlrev_b32_e32 v190, 16, v171
	v_and_b32_e32 v191, 0xffff0000, v171
	v_lshlrev_b32_e32 v192, 16, v172
	v_and_b32_e32 v193, 0xffff0000, v172
	v_lshlrev_b32_e32 v194, 16, v173
	v_and_b32_e32 v195, 0xffff0000, v173
	v_pk_fma_f32 v[204:205], v[102:103], v[188:189], v[204:205]
	v_pk_fma_f32 v[206:207], v[104:105], v[190:191], v[206:207]
	v_pk_fma_f32 v[208:209], v[106:107], v[192:193], v[208:209]
	v_pk_fma_f32 v[210:211], v[108:109], v[194:195], v[210:211]
	v_lshlrev_b32_e32 v188, 16, v174
	v_and_b32_e32 v189, 0xffff0000, v174
	v_lshlrev_b32_e32 v190, 16, v175
	v_and_b32_e32 v191, 0xffff0000, v175
	v_lshlrev_b32_e32 v192, 16, v176
	v_and_b32_e32 v193, 0xffff0000, v176
	v_lshlrev_b32_e32 v194, 16, v177
	v_and_b32_e32 v195, 0xffff0000, v177
	v_pk_fma_f32 v[204:205], v[110:111], v[188:189], v[204:205]
	v_pk_fma_f32 v[206:207], v[112:113], v[190:191], v[206:207]
	v_pk_fma_f32 v[208:209], v[114:115], v[192:193], v[208:209]
	v_pk_fma_f32 v[210:211], v[116:117], v[194:195], v[210:211]
	v_lshlrev_b32_e32 v188, 16, v178
	v_and_b32_e32 v189, 0xffff0000, v178
	v_lshlrev_b32_e32 v190, 16, v179
	v_and_b32_e32 v191, 0xffff0000, v179
	v_lshlrev_b32_e32 v192, 16, v180
	v_and_b32_e32 v193, 0xffff0000, v180
	v_lshlrev_b32_e32 v194, 16, v181
	v_and_b32_e32 v195, 0xffff0000, v181
	v_pk_fma_f32 v[204:205], v[8:9], v[188:189], v[204:205]
	v_pk_fma_f32 v[206:207], v[10:11], v[190:191], v[206:207]
	v_pk_fma_f32 v[208:209], v[12:13], v[192:193], v[208:209]
	v_pk_fma_f32 v[210:211], v[14:15], v[194:195], v[210:211]
	v_mul_f32_e32 v212, 0xbfb8aa3b, v204
	v_mul_f32_e32 v213, 0xbfb8aa3b, v205
	v_mul_f32_e32 v214, 0xbfb8aa3b, v206
	v_mul_f32_e32 v215, 0xbfb8aa3b, v207
	v_mul_f32_e32 v216, 0xbfb8aa3b, v208
	v_mul_f32_e32 v217, 0xbfb8aa3b, v209
	v_mul_f32_e32 v218, 0xbfb8aa3b, v210
	v_mul_f32_e32 v219, 0xbfb8aa3b, v211
	v_pk_mul_f32 v[188:189], v[26:27], v[204:205]
	v_pk_mul_f32 v[190:191], v[26:27], v[206:207]
	v_pk_mul_f32 v[192:193], v[26:27], v[208:209]
	v_pk_mul_f32 v[194:195], v[26:27], v[210:211]
	v_exp_f32_e32 v212, v212
	v_exp_f32_e32 v213, v213
	v_exp_f32_e32 v214, v214
	v_exp_f32_e32 v215, v215
	v_exp_f32_e32 v216, v216
	v_exp_f32_e32 v217, v217
	v_exp_f32_e32 v218, v218
	v_exp_f32_e32 v219, v219
	v_add_f32_e32 v212, 1.0, v212
	v_add_f32_e32 v213, 1.0, v213
	v_add_f32_e32 v214, 1.0, v214
	v_add_f32_e32 v215, 1.0, v215
	v_add_f32_e32 v216, 1.0, v216
	v_add_f32_e32 v217, 1.0, v217
	v_add_f32_e32 v218, 1.0, v218
	v_add_f32_e32 v219, 1.0, v219
	v_rcp_f32_e32 v212, v212
	v_rcp_f32_e32 v213, v213
	v_rcp_f32_e32 v214, v214
	v_rcp_f32_e32 v215, v215
	v_rcp_f32_e32 v216, v216
	v_rcp_f32_e32 v217, v217
	v_rcp_f32_e32 v218, v218
	v_rcp_f32_e32 v219, v219
	v_pk_mul_f32 v[188:189], v[188:189], v[212:213]
	v_pk_mul_f32 v[190:191], v[190:191], v[214:215]
	v_pk_mul_f32 v[192:193], v[192:193], v[216:217]
	v_pk_mul_f32 v[194:195], v[194:195], v[218:219]
	v_cvt_pk_bf16_f32 v196, v188, v189
	v_cvt_pk_bf16_f32 v197, v190, v191
	v_cvt_pk_bf16_f32 v198, v192, v193
	v_cvt_pk_bf16_f32 v199, v194, v195
	ds_write_b128 v54, v[196:199] offset:6528
	v_add_u32_e32 v184, 56, v55
	v_add_u32_e32 v185, -1, v184
	v_mov_b32_e32 v166, 0
	v_mov_b32_e32 v167, 0
	v_mov_b32_e32 v168, 0
	v_mov_b32_e32 v169, 0
	v_mov_b32_e32 v170, 0
	v_mov_b32_e32 v171, 0
	v_mov_b32_e32 v172, 0
	v_mov_b32_e32 v173, 0
	v_mov_b32_e32 v174, 0
	v_mov_b32_e32 v175, 0
	v_mov_b32_e32 v176, 0
	v_mov_b32_e32 v177, 0
	v_mad_i64_i32 v[186:187], s[0:1], v185, s2, v[18:19]
	v_cmp_lt_u32_e64 s[0:1], 2, v184
	s_and_saveexec_b64 s[4:5], s[0:1]
	global_load_dwordx4 v[166:169], v[186:187], off offset:-4096
	s_or_b64 exec, exec, s[4:5]
	v_cmp_lt_u32_e64 s[0:1], 1, v184
	s_and_saveexec_b64 s[4:5], s[0:1]
	global_load_dwordx4 v[170:173], v[186:187], off offset:-2048
	s_or_b64 exec, exec, s[4:5]
	v_cmp_ne_u32_e64 s[0:1], 0, v184
	s_and_saveexec_b64 s[4:5], s[0:1]
	global_load_dwordx4 v[174:177], v[186:187], off
	s_or_b64 exec, exec, s[4:5]
	global_load_dwordx4 v[178:181], v[186:187], off offset:2048
	s_waitcnt vmcnt(12)
; DI unsigned pack2(float a, float b) { const f32x2 v = {a, b}; return __builtin_bit_cast(unsigned, __builtin_convertvector(v, bf16v2)); }
; DI void conv_unit(const u16* __restrict__ PM, const float* __restrict__ conv_w, const float* __restrict__ conv_b, int b, int sl0, int ch, float scale, float* a8) {
;   { const float4 b0 = *(const float4*)(conv_b + ch), b1 = *(const float4*)(conv_b + ch + 4); a8[0] = b0.x; a8[1] = b0.y; a8[2] = b0.z; a8[3] = b0.w; a8[4] = b1.x; a8[5] = b1.y; a8[6] = b1.z; a8[7] = b1.w; }
; #pragma unroll
;   for (int j = 0; j < 4; ++j) {
;     const int sl = sl0 - 3 + j;
;     if (sl >= 0) {
;       const uint4 raw = *(const uint4*)(PM + ((size_t)b * SEQ + sl) * 1024 + ch);
;       float x8[8]; unpack8(raw, x8);
;       const float4 w0 = *(const float4*)(conv_w + j * 1024 + ch), w1 = *(const float4*)(conv_w + j * 1024 + ch + 4);
;       a8[0] += w0.x * x8[0]; a8[1] += w0.y * x8[1]; a8[2] += w0.z * x8[2]; a8[3] += w0.w * x8[3];
;       a8[4] += w1.x * x8[4]; a8[5] += w1.y * x8[5]; a8[6] += w1.z * x8[6]; a8[7] += w1.w * x8[7];
;     }
;   }
; #pragma unroll
;   for (int e = 0; e < 8; ++e) { const float v = a8[e]; a8[e] = scale * v * __builtin_amdgcn_rcpf(1.f + __expf(-v)); }
; }
; DI void mlstmC_pair(const Params& p, char* lds_all, int pair) {
;     ...
;     const int cg8 = ltid & 31, isK = cg8 >> 4, chl = (cg8 & 15) * 8, t = (ltid >> 5) + 8 * i;
;     float a8[8];
;     conv_unit(PM, p.in[5], p.in[6], b, c * 64 + t, (isK ? 512 : 0) + hd * 128 + chl, isK ? 0.08838834764831845f : 1.f, a8);
;     uint4 o; o.x = pack2(a8[0], a8[1]); o.y = pack2(a8[2], a8[3]); o.z = pack2(a8[4], a8[5]); o.w = pack2(a8[6], a8[7]);
;     *(uint4*)((isK ? Ks : Qs) + t * 136 + chl) = o;
	v_lshlrev_b32_e32 v188, 16, v118
	v_and_b32_e32 v189, 0xffff0000, v118
	v_lshlrev_b32_e32 v190, 16, v119
	v_and_b32_e32 v191, 0xffff0000, v119
	v_lshlrev_b32_e32 v192, 16, v120
	v_and_b32_e32 v193, 0xffff0000, v120
	v_lshlrev_b32_e32 v194, 16, v121
	v_and_b32_e32 v195, 0xffff0000, v121
	v_pk_fma_f32 v[204:205], v[94:95], v[188:189], v[4:5]
	v_pk_fma_f32 v[206:207], v[96:97], v[190:191], v[6:7]
	v_pk_fma_f32 v[208:209], v[98:99], v[192:193], v[0:1]
	v_pk_fma_f32 v[210:211], v[100:101], v[194:195], v[2:3]
	v_lshlrev_b32_e32 v188, 16, v122
	v_and_b32_e32 v189, 0xffff0000, v122
	v_lshlrev_b32_e32 v190, 16, v123
	v_and_b32_e32 v191, 0xffff0000, v123
	v_lshlrev_b32_e32 v192, 16, v124
	v_and_b32_e32 v193, 0xffff0000, v124
	v_lshlrev_b32_e32 v194, 16, v125
	v_and_b32_e32 v195, 0xffff0000, v125
	v_pk_fma_f32 v[204:205], v[102:103], v[188:189], v[204:205]
	v_pk_fma_f32 v[206:207], v[104:105], v[190:191], v[206:207]
	v_pk_fma_f32 v[208:209], v[106:107], v[192:193], v[208:209]
	v_pk_fma_f32 v[210:211], v[108:109], v[194:195], v[210:211]
	v_lshlrev_b32_e32 v188, 16, v126
	v_and_b32_e32 v189, 0xffff0000, v126
	v_lshlrev_b32_e32 v190, 16, v127
	v_and_b32_e32 v191, 0xffff0000, v127
	v_lshlrev_b32_e32 v192, 16, v128
	v_and_b32_e32 v193, 0xffff0000, v128
	v_lshlrev_b32_e32 v194, 16, v129
	v_and_b32_e32 v195, 0xffff0000, v129
	v_pk_fma_f32 v[204:205], v[110:111], v[188:189], v[204:205]
	v_pk_fma_f32 v[206:207], v[112:113], v[190:191], v[206:207]
	v_pk_fma_f32 v[208:209], v[114:115], v[192:193], v[208:209]
	v_pk_fma_f32 v[210:211], v[116:117], v[194:195], v[210:211]
	v_lshlrev_b32_e32 v188, 16, v130
	v_and_b32_e32 v189, 0xffff0000, v130
	v_lshlrev_b32_e32 v190, 16, v131
	v_and_b32_e32 v191, 0xffff0000, v131
	v_lshlrev_b32_e32 v192, 16, v132
	v_and_b32_e32 v193, 0xffff0000, v132
	v_lshlrev_b32_e32 v194, 16, v133
	v_and_b32_e32 v195, 0xffff0000, v133
	v_pk_fma_f32 v[204:205], v[8:9], v[188:189], v[204:205]
	v_pk_fma_f32 v[206:207], v[10:11], v[190:191], v[206:207]
	v_pk_fma_f32 v[208:209], v[12:13], v[192:193], v[208:209]
	v_pk_fma_f32 v[210:211], v[14:15], v[194:195], v[210:211]
	v_mul_f32_e32 v212, 0xbfb8aa3b, v204
	v_mul_f32_e32 v213, 0xbfb8aa3b, v205
	v_mul_f32_e32 v214, 0xbfb8aa3b, v206
	v_mul_f32_e32 v215, 0xbfb8aa3b, v207
	v_mul_f32_e32 v216, 0xbfb8aa3b, v208
	v_mul_f32_e32 v217, 0xbfb8aa3b, v209
	v_mul_f32_e32 v218, 0xbfb8aa3b, v210
	v_mul_f32_e32 v219, 0xbfb8aa3b, v211
	v_pk_mul_f32 v[188:189], v[26:27], v[204:205]
	v_pk_mul_f32 v[190:191], v[26:27], v[206:207]
	v_pk_mul_f32 v[192:193], v[26:27], v[208:209]
	v_pk_mul_f32 v[194:195], v[26:27], v[210:211]
	v_exp_f32_e32 v212, v212
	v_exp_f32_e32 v213, v213
	v_exp_f32_e32 v214, v214
	v_exp_f32_e32 v215, v215
	v_exp_f32_e32 v216, v216
	v_exp_f32_e32 v217, v217
	v_exp_f32_e32 v218, v218
	v_exp_f32_e32 v219, v219
	v_add_f32_e32 v212, 1.0, v212
	v_add_f32_e32 v213, 1.0, v213
	v_add_f32_e32 v214, 1.0, v214
	v_add_f32_e32 v215, 1.0, v215
	v_add_f32_e32 v216, 1.0, v216
	v_add_f32_e32 v217, 1.0, v217
	v_add_f32_e32 v218, 1.0, v218
	v_add_f32_e32 v219, 1.0, v219
	v_rcp_f32_e32 v212, v212
	v_rcp_f32_e32 v213, v213
	v_rcp_f32_e32 v214, v214
	v_rcp_f32_e32 v215, v215
	v_rcp_f32_e32 v216, v216
	v_rcp_f32_e32 v217, v217
	v_rcp_f32_e32 v218, v218
	v_rcp_f32_e32 v219, v219
	v_pk_mul_f32 v[188:189], v[188:189], v[212:213]
	v_pk_mul_f32 v[190:191], v[190:191], v[214:215]
	v_pk_mul_f32 v[192:193], v[192:193], v[216:217]
	v_pk_mul_f32 v[194:195], v[194:195], v[218:219]
	v_cvt_pk_bf16_f32 v196, v188, v189
	v_cvt_pk_bf16_f32 v197, v190, v191
	v_cvt_pk_bf16_f32 v198, v192, v193
	v_cvt_pk_bf16_f32 v199, v194, v195
	ds_write_b128 v54, v[196:199] offset:8704
	s_waitcnt vmcnt(8)
	v_lshlrev_b32_e32 v188, 16, v134
	v_and_b32_e32 v189, 0xffff0000, v134
	v_lshlrev_b32_e32 v190, 16, v135
	v_and_b32_e32 v191, 0xffff0000, v135
	v_lshlrev_b32_e32 v192, 16, v136
	v_and_b32_e32 v193, 0xffff0000, v136
	v_lshlrev_b32_e32 v194, 16, v137
	v_and_b32_e32 v195, 0xffff0000, v137
	v_pk_fma_f32 v[204:205], v[94:95], v[188:189], v[4:5]
	v_pk_fma_f32 v[206:207], v[96:97], v[190:191], v[6:7]
	v_pk_fma_f32 v[208:209], v[98:99], v[192:193], v[0:1]
	v_pk_fma_f32 v[210:211], v[100:101], v[194:195], v[2:3]
	v_lshlrev_b32_e32 v188, 16, v138
	v_and_b32_e32 v189, 0xffff0000, v138
	v_lshlrev_b32_e32 v190, 16, v139
	v_and_b32_e32 v191, 0xffff0000, v139
	v_lshlrev_b32_e32 v192, 16, v140
	v_and_b32_e32 v193, 0xffff0000, v140
	v_lshlrev_b32_e32 v194, 16, v141
	v_and_b32_e32 v195, 0xffff0000, v141
	v_pk_fma_f32 v[204:205], v[102:103], v[188:189], v[204:205]
	v_pk_fma_f32 v[206:207], v[104:105], v[190:191], v[206:207]
	v_pk_fma_f32 v[208:209], v[106:107], v[192:193], v[208:209]
	v_pk_fma_f32 v[210:211], v[108:109], v[194:195], v[210:211]
	v_lshlrev_b32_e32 v188, 16, v142
	v_and_b32_e32 v189, 0xffff0000, v142
	v_lshlrev_b32_e32 v190, 16, v143
	v_and_b32_e32 v191, 0xffff0000, v143
	v_lshlrev_b32_e32 v192, 16, v144
	v_and_b32_e32 v193, 0xffff0000, v144
	v_lshlrev_b32_e32 v194, 16, v145
	v_and_b32_e32 v195, 0xffff0000, v145
	v_pk_fma_f32 v[204:205], v[110:111], v[188:189], v[204:205]
	v_pk_fma_f32 v[206:207], v[112:113], v[190:191], v[206:207]
	v_pk_fma_f32 v[208:209], v[114:115], v[192:193], v[208:209]
	v_pk_fma_f32 v[210:211], v[116:117], v[194:195], v[210:211]
	v_lshlrev_b32_e32 v188, 16, v146
	v_and_b32_e32 v189, 0xffff0000, v146
	v_lshlrev_b32_e32 v190, 16, v147
	v_and_b32_e32 v191, 0xffff0000, v147
	v_lshlrev_b32_e32 v192, 16, v148
	v_and_b32_e32 v193, 0xffff0000, v148
	v_lshlrev_b32_e32 v194, 16, v149
	v_and_b32_e32 v195, 0xffff0000, v149
	v_pk_fma_f32 v[204:205], v[8:9], v[188:189], v[204:205]
	v_pk_fma_f32 v[206:207], v[10:11], v[190:191], v[206:207]
; DI unsigned pack2(float a, float b) { const f32x2 v = {a, b}; return __builtin_bit_cast(unsigned, __builtin_convertvector(v, bf16v2)); }
; DI void conv_unit(const u16* __restrict__ PM, const float* __restrict__ conv_w, const float* __restrict__ conv_b, int b, int sl0, int ch, float scale, float* a8) {
;   { const float4 b0 = *(const float4*)(conv_b + ch), b1 = *(const float4*)(conv_b + ch + 4); a8[0] = b0.x; a8[1] = b0.y; a8[2] = b0.z; a8[3] = b0.w; a8[4] = b1.x; a8[5] = b1.y; a8[6] = b1.z; a8[7] = b1.w; }
; #pragma unroll
;   for (int j = 0; j < 4; ++j) {
;     const int sl = sl0 - 3 + j;
;     if (sl >= 0) {
;       const uint4 raw = *(const uint4*)(PM + ((size_t)b * SEQ + sl) * 1024 + ch);
;       float x8[8]; unpack8(raw, x8);
;       const float4 w0 = *(const float4*)(conv_w + j * 1024 + ch), w1 = *(const float4*)(conv_w + j * 1024 + ch + 4);
;       a8[0] += w0.x * x8[0]; a8[1] += w0.y * x8[1]; a8[2] += w0.z * x8[2]; a8[3] += w0.w * x8[3];
;       a8[4] += w1.x * x8[4]; a8[5] += w1.y * x8[5]; a8[6] += w1.z * x8[6]; a8[7] += w1.w * x8[7];
;     }
;   }
; #pragma unroll
;   for (int e = 0; e < 8; ++e) { const float v = a8[e]; a8[e] = scale * v * __builtin_amdgcn_rcpf(1.f + __expf(-v)); }
; }
; DI void mlstmC_pair(const Params& p, char* lds_all, int pair) {
;     ...
;     const int cg8 = ltid & 31, isK = cg8 >> 4, chl = (cg8 & 15) * 8, t = (ltid >> 5) + 8 * i;
;     float a8[8];
;     conv_unit(PM, p.in[5], p.in[6], b, c * 64 + t, (isK ? 512 : 0) + hd * 128 + chl, isK ? 0.08838834764831845f : 1.f, a8);
;     uint4 o; o.x = pack2(a8[0], a8[1]); o.y = pack2(a8[2], a8[3]); o.z = pack2(a8[4], a8[5]); o.w = pack2(a8[6], a8[7]);
;     *(uint4*)((isK ? Ks : Qs) + t * 136 + chl) = o;
	v_pk_fma_f32 v[208:209], v[12:13], v[192:193], v[208:209]
	v_pk_fma_f32 v[210:211], v[14:15], v[194:195], v[210:211]
	v_mul_f32_e32 v212, 0xbfb8aa3b, v204
	v_mul_f32_e32 v213, 0xbfb8aa3b, v205
	v_mul_f32_e32 v214, 0xbfb8aa3b, v206
	v_mul_f32_e32 v215, 0xbfb8aa3b, v207
	v_mul_f32_e32 v216, 0xbfb8aa3b, v208
	v_mul_f32_e32 v217, 0xbfb8aa3b, v209
	v_mul_f32_e32 v218, 0xbfb8aa3b, v210
	v_mul_f32_e32 v219, 0xbfb8aa3b, v211
	v_pk_mul_f32 v[188:189], v[26:27], v[204:205]
	v_pk_mul_f32 v[190:191], v[26:27], v[206:207]
	v_pk_mul_f32 v[192:193], v[26:27], v[208:209]
	v_pk_mul_f32 v[194:195], v[26:27], v[210:211]
	v_exp_f32_e32 v212, v212
	v_exp_f32_e32 v213, v213
	v_exp_f32_e32 v214, v214
	v_exp_f32_e32 v215, v215
	v_exp_f32_e32 v216, v216
	v_exp_f32_e32 v217, v217
	v_exp_f32_e32 v218, v218
	v_exp_f32_e32 v219, v219
	v_add_f32_e32 v212, 1.0, v212
	v_add_f32_e32 v213, 1.0, v213
	v_add_f32_e32 v214, 1.0, v214
	v_add_f32_e32 v215, 1.0, v215
	v_add_f32_e32 v216, 1.0, v216
	v_add_f32_e32 v217, 1.0, v217
	v_add_f32_e32 v218, 1.0, v218
	v_add_f32_e32 v219, 1.0, v219
	v_rcp_f32_e32 v212, v212
	v_rcp_f32_e32 v213, v213
	v_rcp_f32_e32 v214, v214
	v_rcp_f32_e32 v215, v215
	v_rcp_f32_e32 v216, v216
	v_rcp_f32_e32 v217, v217
	v_rcp_f32_e32 v218, v218
	v_rcp_f32_e32 v219, v219
	v_pk_mul_f32 v[188:189], v[188:189], v[212:213]
	v_pk_mul_f32 v[190:191], v[190:191], v[214:215]
	v_pk_mul_f32 v[192:193], v[192:193], v[216:217]
	v_pk_mul_f32 v[194:195], v[194:195], v[218:219]
	v_cvt_pk_bf16_f32 v196, v188, v189
	v_cvt_pk_bf16_f32 v197, v190, v191
	v_cvt_pk_bf16_f32 v198, v192, v193
	v_cvt_pk_bf16_f32 v199, v194, v195
	ds_write_b128 v54, v[196:199] offset:10880
	s_waitcnt vmcnt(4)
	v_lshlrev_b32_e32 v188, 16, v150
	v_and_b32_e32 v189, 0xffff0000, v150
	v_lshlrev_b32_e32 v190, 16, v151
	v_and_b32_e32 v191, 0xffff0000, v151
	v_lshlrev_b32_e32 v192, 16, v152
	v_and_b32_e32 v193, 0xffff0000, v152
	v_lshlrev_b32_e32 v194, 16, v153
	v_and_b32_e32 v195, 0xffff0000, v153
	v_pk_fma_f32 v[204:205], v[94:95], v[188:189], v[4:5]
	v_pk_fma_f32 v[206:207], v[96:97], v[190:191], v[6:7]
	v_pk_fma_f32 v[208:209], v[98:99], v[192:193], v[0:1]
	v_pk_fma_f32 v[210:211], v[100:101], v[194:195], v[2:3]
	v_lshlrev_b32_e32 v188, 16, v154
	v_and_b32_e32 v189, 0xffff0000, v154
	v_lshlrev_b32_e32 v190, 16, v155
	v_and_b32_e32 v191, 0xffff0000, v155
	v_lshlrev_b32_e32 v192, 16, v156
	v_and_b32_e32 v193, 0xffff0000, v156
	v_lshlrev_b32_e32 v194, 16, v157
	v_and_b32_e32 v195, 0xffff0000, v157
	v_pk_fma_f32 v[204:205], v[102:103], v[188:189], v[204:205]
	v_pk_fma_f32 v[206:207], v[104:105], v[190:191], v[206:207]
	v_pk_fma_f32 v[208:209], v[106:107], v[192:193], v[208:209]
	v_pk_fma_f32 v[210:211], v[108:109], v[194:195], v[210:211]
	v_lshlrev_b32_e32 v188, 16, v158
	v_and_b32_e32 v189, 0xffff0000, v158
	v_lshlrev_b32_e32 v190, 16, v159
	v_and_b32_e32 v191, 0xffff0000, v159
	v_lshlrev_b32_e32 v192, 16, v160
	v_and_b32_e32 v193, 0xffff0000, v160
	v_lshlrev_b32_e32 v194, 16, v161
	v_and_b32_e32 v195, 0xffff0000, v161
	v_pk_fma_f32 v[204:205], v[110:111], v[188:189], v[204:205]
	v_pk_fma_f32 v[206:207], v[112:113], v[190:191], v[206:207]
	v_pk_fma_f32 v[208:209], v[114:115], v[192:193], v[208:209]
	v_pk_fma_f32 v[210:211], v[116:117], v[194:195], v[210:211]
	v_lshlrev_b32_e32 v188, 16, v162
	v_and_b32_e32 v189, 0xffff0000, v162
	v_lshlrev_b32_e32 v190, 16, v163
	v_and_b32_e32 v191, 0xffff0000, v163
	v_lshlrev_b32_e32 v192, 16, v164
	v_and_b32_e32 v193, 0xffff0000, v164
	v_lshlrev_b32_e32 v194, 16, v165
	v_and_b32_e32 v195, 0xffff0000, v165
	v_pk_fma_f32 v[204:205], v[8:9], v[188:189], v[204:205]
	v_pk_fma_f32 v[206:207], v[10:11], v[190:191], v[206:207]
	v_pk_fma_f32 v[208:209], v[12:13], v[192:193], v[208:209]
	v_pk_fma_f32 v[210:211], v[14:15], v[194:195], v[210:211]
	v_mul_f32_e32 v212, 0xbfb8aa3b, v204
	v_mul_f32_e32 v213, 0xbfb8aa3b, v205
	v_mul_f32_e32 v214, 0xbfb8aa3b, v206
	v_mul_f32_e32 v215, 0xbfb8aa3b, v207
	v_mul_f32_e32 v216, 0xbfb8aa3b, v208
	v_mul_f32_e32 v217, 0xbfb8aa3b, v209
	v_mul_f32_e32 v218, 0xbfb8aa3b, v210
	v_mul_f32_e32 v219, 0xbfb8aa3b, v211
	v_pk_mul_f32 v[188:189], v[26:27], v[204:205]
	v_pk_mul_f32 v[190:191], v[26:27], v[206:207]
	v_pk_mul_f32 v[192:193], v[26:27], v[208:209]
	v_pk_mul_f32 v[194:195], v[26:27], v[210:211]
	v_exp_f32_e32 v212, v212
	v_exp_f32_e32 v213, v213
	v_exp_f32_e32 v214, v214
	v_exp_f32_e32 v215, v215
	v_exp_f32_e32 v216, v216
	v_exp_f32_e32 v217, v217
	v_exp_f32_e32 v218, v218
	v_exp_f32_e32 v219, v219
	v_add_f32_e32 v212, 1.0, v212
	v_add_f32_e32 v213, 1.0, v213
	v_add_f32_e32 v214, 1.0, v214
	v_add_f32_e32 v215, 1.0, v215
	v_add_f32_e32 v216, 1.0, v216
	v_add_f32_e32 v217, 1.0, v217
	v_add_f32_e32 v218, 1.0, v218
	v_add_f32_e32 v219, 1.0, v219
	v_rcp_f32_e32 v212, v212
	v_rcp_f32_e32 v213, v213
	v_rcp_f32_e32 v214, v214
	v_rcp_f32_e32 v215, v215
	v_rcp_f32_e32 v216, v216
	v_rcp_f32_e32 v217, v217
	v_rcp_f32_e32 v218, v218
	v_rcp_f32_e32 v219, v219
	v_pk_mul_f32 v[188:189], v[188:189], v[212:213]
	v_pk_mul_f32 v[190:191], v[190:191], v[214:215]
	v_pk_mul_f32 v[192:193], v[192:193], v[216:217]
	v_pk_mul_f32 v[194:195], v[194:195], v[218:219]
	v_cvt_pk_bf16_f32 v196, v188, v189
	v_cvt_pk_bf16_f32 v197, v190, v191
	v_cvt_pk_bf16_f32 v198, v192, v193
	v_cvt_pk_bf16_f32 v199, v194, v195
	ds_write_b128 v54, v[196:199] offset:13056
	s_waitcnt vmcnt(0)
; DI unsigned pack2(float a, float b) { const f32x2 v = {a, b}; return __builtin_bit_cast(unsigned, __builtin_convertvector(v, bf16v2)); }
; DI void conv_unit(const u16* __restrict__ PM, const float* __restrict__ conv_w, const float* __restrict__ conv_b, int b, int sl0, int ch, float scale, float* a8) {
;   { const float4 b0 = *(const float4*)(conv_b + ch), b1 = *(const float4*)(conv_b + ch + 4); a8[0] = b0.x; a8[1] = b0.y; a8[2] = b0.z; a8[3] = b0.w; a8[4] = b1.x; a8[5] = b1.y; a8[6] = b1.z; a8[7] = b1.w; }
; #pragma unroll
;   for (int j = 0; j < 4; ++j) {
;     const int sl = sl0 - 3 + j;
;     if (sl >= 0) {
;       const uint4 raw = *(const uint4*)(PM + ((size_t)b * SEQ + sl) * 1024 + ch);
;       float x8[8]; unpack8(raw, x8);
;       const float4 w0 = *(const float4*)(conv_w + j * 1024 + ch), w1 = *(const float4*)(conv_w + j * 1024 + ch + 4);
;       a8[0] += w0.x * x8[0]; a8[1] += w0.y * x8[1]; a8[2] += w0.z * x8[2]; a8[3] += w0.w * x8[3];
;       a8[4] += w1.x * x8[4]; a8[5] += w1.y * x8[5]; a8[6] += w1.z * x8[6]; a8[7] += w1.w * x8[7];
;     }
;   }
; #pragma unroll
;   for (int e = 0; e < 8; ++e) { const float v = a8[e]; a8[e] = scale * v * __builtin_amdgcn_rcpf(1.f + __expf(-v)); }
; }
; DI void mlstmC_pair(const Params& p, char* lds_all, int pair) {
;     ...
;     uint4 o; o.x = pack2(a8[0], a8[1]); o.y = pack2(a8[2], a8[3]); o.z = pack2(a8[4], a8[5]); o.w = pack2(a8[6], a8[7]);
;     *(uint4*)((isK ? Ks : Qs) + t * 136 + chl) = o;
;   }
;   for (int i = 0; i < 4; ++i) {
;     const int q = ltid + 256 * i, e = q >> 3, s8 = (q & 7) * 8;
;     *(uint4*)(VTs + e * 72 + s8) = *(const uint4*)(VTm + ((size_t)(bh * 128 + e)) * SEQ + c * 64 + s8);
;   }
	v_lshlrev_b32_e32 v188, 16, v166
	v_and_b32_e32 v189, 0xffff0000, v166
	v_lshlrev_b32_e32 v190, 16, v167
	v_and_b32_e32 v191, 0xffff0000, v167
	v_lshlrev_b32_e32 v192, 16, v168
	v_and_b32_e32 v193, 0xffff0000, v168
	v_lshlrev_b32_e32 v194, 16, v169
	v_and_b32_e32 v195, 0xffff0000, v169
	v_pk_fma_f32 v[204:205], v[94:95], v[188:189], v[4:5]
	v_pk_fma_f32 v[206:207], v[96:97], v[190:191], v[6:7]
	v_pk_fma_f32 v[208:209], v[98:99], v[192:193], v[0:1]
	v_pk_fma_f32 v[210:211], v[100:101], v[194:195], v[2:3]
	v_lshlrev_b32_e32 v188, 16, v170
	v_and_b32_e32 v189, 0xffff0000, v170
	v_lshlrev_b32_e32 v190, 16, v171
	v_and_b32_e32 v191, 0xffff0000, v171
	v_lshlrev_b32_e32 v192, 16, v172
	v_and_b32_e32 v193, 0xffff0000, v172
	v_lshlrev_b32_e32 v194, 16, v173
	v_and_b32_e32 v195, 0xffff0000, v173
	v_pk_fma_f32 v[204:205], v[102:103], v[188:189], v[204:205]
	v_pk_fma_f32 v[206:207], v[104:105], v[190:191], v[206:207]
	v_pk_fma_f32 v[208:209], v[106:107], v[192:193], v[208:209]
	v_pk_fma_f32 v[210:211], v[108:109], v[194:195], v[210:211]
	v_lshlrev_b32_e32 v188, 16, v174
	v_and_b32_e32 v189, 0xffff0000, v174
	v_lshlrev_b32_e32 v190, 16, v175
	v_and_b32_e32 v191, 0xffff0000, v175
	v_lshlrev_b32_e32 v192, 16, v176
	v_and_b32_e32 v193, 0xffff0000, v176
	v_lshlrev_b32_e32 v194, 16, v177
	v_and_b32_e32 v195, 0xffff0000, v177
	v_pk_fma_f32 v[204:205], v[110:111], v[188:189], v[204:205]
	v_pk_fma_f32 v[206:207], v[112:113], v[190:191], v[206:207]
	v_pk_fma_f32 v[208:209], v[114:115], v[192:193], v[208:209]
	v_pk_fma_f32 v[210:211], v[116:117], v[194:195], v[210:211]
	v_lshlrev_b32_e32 v188, 16, v178
	v_and_b32_e32 v189, 0xffff0000, v178
	v_lshlrev_b32_e32 v190, 16, v179
	v_and_b32_e32 v191, 0xffff0000, v179
	v_lshlrev_b32_e32 v192, 16, v180
	v_and_b32_e32 v193, 0xffff0000, v180
	v_lshlrev_b32_e32 v194, 16, v181
	v_and_b32_e32 v195, 0xffff0000, v181
	v_pk_fma_f32 v[204:205], v[8:9], v[188:189], v[204:205]
	v_pk_fma_f32 v[206:207], v[10:11], v[190:191], v[206:207]
	v_pk_fma_f32 v[208:209], v[12:13], v[192:193], v[208:209]
	v_pk_fma_f32 v[210:211], v[14:15], v[194:195], v[210:211]
	v_mul_f32_e32 v212, 0xbfb8aa3b, v204
	v_mul_f32_e32 v213, 0xbfb8aa3b, v205
	v_mul_f32_e32 v214, 0xbfb8aa3b, v206
	v_mul_f32_e32 v215, 0xbfb8aa3b, v207
	v_mul_f32_e32 v216, 0xbfb8aa3b, v208
	v_mul_f32_e32 v217, 0xbfb8aa3b, v209
	v_mul_f32_e32 v218, 0xbfb8aa3b, v210
	v_mul_f32_e32 v219, 0xbfb8aa3b, v211
	v_pk_mul_f32 v[188:189], v[26:27], v[204:205]
	v_pk_mul_f32 v[190:191], v[26:27], v[206:207]
	v_pk_mul_f32 v[192:193], v[26:27], v[208:209]
	v_pk_mul_f32 v[194:195], v[26:27], v[210:211]
	v_exp_f32_e32 v212, v212
	v_exp_f32_e32 v213, v213
	v_exp_f32_e32 v214, v214
	v_exp_f32_e32 v215, v215
	v_exp_f32_e32 v216, v216
	v_exp_f32_e32 v217, v217
	v_exp_f32_e32 v218, v218
	v_exp_f32_e32 v219, v219
	v_add_f32_e32 v212, 1.0, v212
	v_add_f32_e32 v213, 1.0, v213
	v_add_f32_e32 v214, 1.0, v214
	v_add_f32_e32 v215, 1.0, v215
	v_add_f32_e32 v216, 1.0, v216
	v_add_f32_e32 v217, 1.0, v217
	v_add_f32_e32 v218, 1.0, v218
	v_add_f32_e32 v219, 1.0, v219
	v_rcp_f32_e32 v212, v212
	v_rcp_f32_e32 v213, v213
	v_rcp_f32_e32 v214, v214
	v_rcp_f32_e32 v215, v215
	v_rcp_f32_e32 v216, v216
	v_rcp_f32_e32 v217, v217
	v_rcp_f32_e32 v218, v218
	v_rcp_f32_e32 v219, v219
	v_pk_mul_f32 v[188:189], v[188:189], v[212:213]
	v_pk_mul_f32 v[190:191], v[190:191], v[214:215]
	v_pk_mul_f32 v[192:193], v[192:193], v[216:217]
	v_pk_mul_f32 v[194:195], v[194:195], v[218:219]
	v_cvt_pk_bf16_f32 v196, v188, v189
	v_cvt_pk_bf16_f32 v197, v190, v191
	v_cvt_pk_bf16_f32 v198, v192, v193
	v_cvt_pk_bf16_f32 v199, v194, v195
	ds_write_b128 v54, v[196:199] offset:15232
.LBB0_580:
	v_lshlrev_b32_e32 v20, 7, v53
	v_lshlrev_b32_e32 v2, 1, v52
	v_lshl_add_u64 v[0:1], s[56:57], 0, v[20:21]
	v_and_b32_e32 v20, 0x70, v2
	v_lshrrev_b32_e32 v2, 3, v42
	s_movk_i32 s0, 0xff80
	v_and_or_b32 v6, v45, s0, v2
	v_ashrrev_i32_e32 v7, 31, v6
	v_lshl_add_u64 v[4:5], v[0:1], 0, v[20:21]
	v_lshlrev_b64 v[0:1], 14, v[6:7]
	v_lshl_add_u64 v[0:1], v[4:5], 0, v[0:1]
	v_mul_u32_u24_e32 v2, 0x90, v2
	v_add3_u32 v7, v51, v20, v2
	global_load_dwordx4 v[0:3], v[0:1], off
	v_lshlrev_b32_e32 v36, 6, v53
	v_and_b32_e32 v26, 63, v46
	v_cmp_gt_u32_e64 s[0:1], 64, v42
	v_lshlrev_b64 v[22:23], 13, v[16:17]
	v_mbcnt_hi_u32_b32 v27, -1, v203
	v_or_b32_e32 v184, 32, v6
	v_ashrrev_i32_e32 v185, 31, v184
	v_lshlrev_b64 v[184:185], 14, v[184:185]
	v_lshl_add_u64 v[184:185], v[4:5], 0, v[184:185]
	global_load_dwordx4 v[118:121], v[184:185], off
	v_or_b32_e32 v184, 64, v6
	v_ashrrev_i32_e32 v185, 31, v184
	v_lshlrev_b64 v[184:185], 14, v[184:185]
	v_lshl_add_u64 v[184:185], v[4:5], 0, v[184:185]
	global_load_dwordx4 v[122:125], v[184:185], off
	v_or_b32_e32 v184, 0x60, v6
	v_ashrrev_i32_e32 v185, 31, v184
	v_lshlrev_b64 v[184:185], 14, v[184:185]
	v_lshl_add_u64 v[184:185], v[4:5], 0, v[184:185]
	global_load_dwordx4 v[126:129], v[184:185], off
	s_waitcnt vmcnt(3)
	ds_write_b128 v7, v[0:3] offset:34816
	s_waitcnt vmcnt(2)
	ds_write_b128 v7, v[118:121] offset:39424
	s_waitcnt vmcnt(1)
	ds_write_b128 v7, v[122:125] offset:44032
	s_waitcnt vmcnt(0)
	ds_write_b128 v7, v[126:129] offset:48640
	s_and_saveexec_b64 s[6:7], s[0:1]
	s_cbranch_execz .LBB0_582
; DI float scan_sum(float v, int lane) { for (int o = 1; o < 64; o <<= 1) { float tv = __shfl_up(v, o); if (lane >= o) v += tv; } return v; }
; DI float log_sigmoid(float f) { return fminf(f, 0.f) - log1pf(expf(-fabsf(f))); }
; DI void mlstmC_pair(const Params& p, char* lds_all, int pair) {
;     ...
;   if (lwave == 0) {
;     const size_t row = (size_t)b * SEQ + c * 64 + lane;
;     const float ig = G[row * 8 + hd] + p.in[7][hd], fg = G[row * 8 + 4 + hd] + p.in[8][hd];
;     const float bc = scan_sum(log_sigmoid(fg), lane);
	v_or_b32_e32 v0, v22, v26
	v_or_b32_e32 v0, v0, v36
	v_mov_b32_e32 v1, v23
	v_lshlrev_b64 v[0:1], 5, v[0:1]
	v_lshl_add_u64 v[0:1], s[52:53], 0, v[0:1]
	v_lshlrev_b32_e32 v20, 2, v44
	v_lshl_add_u64 v[2:3], v[0:1], 0, v[20:21]
	global_load_dword v0, v[2:3], off
	global_load_dword v1, v20, s[66:67]
	s_mov_b32 s0, 0xb2a5705f
	s_waitcnt vmcnt(0)
	v_add_f32_e32 v0, v0, v1
	global_load_dword v1, v[2:3], off offset:16
	s_nop 0
	global_load_dword v2, v20, s[36:37]
	s_waitcnt vmcnt(0)
	v_add_f32_e32 v1, v1, v2
	v_mul_f32_e64 v2, |v1|, s19
	v_fma_f32 v3, |v1|, s19, -v2
	v_rndne_f32_e32 v5, v2
	v_fma_f32 v3, |v1|, s0, v3
	v_sub_f32_e32 v2, v2, v5
	v_add_f32_e32 v2, v2, v3
	v_exp_f32_e32 v2, v2
	v_cvt_i32_f32_e32 v3, v5
	v_cmp_ngt_f32_e64 s[0:1], |v1|, s20
	v_min_f32_e32 v4, 0, v1
	v_ldexp_f32 v2, v2, v3
	v_cndmask_b32_e64 v2, 0, v2, s[0:1]
	v_cmp_nlt_f32_e64 s[0:1], |v1|, s21
	s_nop 1
	v_cndmask_b32_e64 v1, v50, v2, s[0:1]
	v_add_f32_e32 v5, 1.0, v1
	v_add_f32_e32 v2, -1.0, v5
	v_sub_f32_e32 v3, v2, v5
	v_add_f32_e32 v3, 1.0, v3
	v_sub_f32_e32 v2, v1, v2
	v_add_f32_e32 v6, v2, v3
	v_frexp_mant_f32_e32 v2, v5
	s_mov_b32 s0, 0x3f2aaaab
	v_cmp_gt_f32_e64 s[0:1], s0, v2
	v_cvt_f64_f32_e32 v[2:3], v5
	v_frexp_exp_i32_f64_e32 v2, v[2:3]
	v_subbrev_co_u32_e64 v2, s[0:1], 0, v2, s[0:1]
	v_sub_u32_e32 v3, 0, v2
	v_ldexp_f32 v5, v5, v3
	v_ldexp_f32 v3, v6, v3
	v_add_f32_e32 v6, -1.0, v5
	v_add_f32_e32 v7, 1.0, v6
	v_sub_f32_e32 v7, v5, v7
	v_add_f32_e32 v7, v3, v7
	v_add_f32_e32 v8, v6, v7
	v_sub_f32_e32 v6, v6, v8
	v_add_f32_e32 v6, v7, v6
	v_add_f32_e32 v7, 1.0, v5
	v_add_f32_e32 v9, -1.0, v7
	v_sub_f32_e32 v5, v5, v9
	v_add_f32_e32 v3, v3, v5
	v_add_f32_e32 v5, v7, v3
	v_sub_f32_e32 v7, v7, v5
	v_add_f32_e32 v3, v3, v7
	v_rcp_f32_e32 v7, v5
	v_cvt_f32_i32_e32 v2, v2
	s_mov_b32 s0, 0x3f317218
	v_mul_f32_e32 v9, v8, v7
	v_mul_f32_e32 v10, v5, v9
	v_fma_f32 v11, v9, v5, -v10
	v_fmac_f32_e32 v11, v9, v3
	v_add_f32_e32 v12, v10, v11
	v_sub_f32_e32 v13, v8, v12
	v_sub_f32_e32 v8, v8, v13
	v_sub_f32_e32 v10, v12, v10
	v_sub_f32_e32 v8, v8, v12
	v_add_f32_e32 v6, v6, v8
	v_sub_f32_e32 v8, v10, v11
	v_add_f32_e32 v6, v8, v6
	v_add_f32_e32 v8, v13, v6
	v_mul_f32_e32 v10, v7, v8
	v_mul_f32_e32 v11, v5, v10
	v_fma_f32 v5, v10, v5, -v11
	v_fmac_f32_e32 v5, v10, v3
	v_sub_f32_e32 v3, v13, v8
	v_add_f32_e32 v3, v6, v3
	v_add_f32_e32 v6, v11, v5
	v_sub_f32_e32 v12, v8, v6
	v_sub_f32_e32 v8, v8, v12
	v_sub_f32_e32 v11, v6, v11
	v_sub_f32_e32 v6, v8, v6
	v_add_f32_e32 v3, v3, v6
	v_sub_f32_e32 v5, v11, v5
	v_add_f32_e32 v3, v5, v3
	v_add_f32_e32 v5, v9, v10
	v_add_f32_e32 v3, v12, v3
	v_sub_f32_e32 v6, v5, v9
	v_mul_f32_e32 v3, v7, v3
	v_sub_f32_e32 v6, v10, v6
	v_add_f32_e32 v3, v6, v3
	v_mul_f32_e32 v9, 0x3f317218, v2
	v_add_f32_e32 v6, v5, v3
	v_fma_f32 v10, v2, s0, -v9
	v_mul_f32_e32 v7, v6, v6
	v_fmac_f32_e32 v10, 0xb102e308, v2
	v_sub_f32_e32 v2, v6, v5
	v_fmamk_f32 v8, v7, 0x3e9b6dac, v49
	v_sub_f32_e32 v2, v3, v2
	v_add_f32_e32 v3, v9, v10
	v_fmaak_f32 v8, v7, v8, 0x3f2aaada
	v_sub_f32_e32 v5, v3, v9
	v_ldexp_f32 v9, v6, 1
	v_mul_f32_e32 v6, v6, v7
	v_mul_f32_e32 v6, v6, v8
	v_add_f32_e32 v7, v9, v6
	v_sub_f32_e32 v8, v7, v9
	v_ldexp_f32 v2, v2, 1
	v_sub_f32_e32 v6, v6, v8
	v_add_f32_e32 v2, v2, v6
	v_add_f32_e32 v6, v7, v2
	v_sub_f32_e32 v7, v6, v7
	v_sub_f32_e32 v2, v2, v7
	v_add_f32_e32 v7, v3, v6
	v_sub_f32_e32 v8, v7, v3
	v_sub_f32_e32 v9, v7, v8
	v_sub_f32_e32 v5, v10, v5
	v_sub_f32_e32 v3, v3, v9
	v_sub_f32_e32 v6, v6, v8
	v_add_f32_e32 v3, v6, v3
	v_add_f32_e32 v6, v5, v2
	v_sub_f32_e32 v8, v6, v5
	v_sub_f32_e32 v9, v6, v8
	v_sub_f32_e32 v5, v5, v9
	v_sub_f32_e32 v2, v2, v8
	v_add_f32_e32 v3, v6, v3
	v_add_f32_e32 v2, v2, v5
	v_add_f32_e32 v5, v7, v3
	v_sub_f32_e32 v6, v5, v7
	v_sub_f32_e32 v3, v3, v6
	v_add_f32_e32 v2, v2, v3
	s_mov_b32 s0, 0x7f800000
	v_add_f32_e32 v2, v5, v2
	v_cmp_neq_f32_e64 s[0:1], s0, v1
	s_nop 1
	v_cndmask_b32_e64 v2, v50, v2, s[0:1]
	s_mov_b32 s0, 0x33800000
	v_cmp_lt_f32_e64 s[0:1], |v1|, s0
	s_nop 1
	v_cndmask_b32_e64 v1, v2, v1, s[0:1]
	v_sub_f32_e32 v3, v4, v1
	v_and_b32_e32 v2, 64, v27
	v_add_u32_e32 v1, -1, v27
	v_cmp_lt_i32_e64 s[0:1], v1, v2
	s_nop 1
	v_cndmask_b32_e64 v1, v1, v27, s[0:1]
	v_lshlrev_b32_e32 v1, 2, v1
	ds_bpermute_b32 v4, v1, v3
	v_cmp_eq_u32_e64 s[0:1], 0, v26
	s_waitcnt lgkmcnt(0)
; DI float log_sigmoid(float f) { return fminf(f, 0.f) - log1pf(expf(-fabsf(f))); }
; DI float scan_sum(float v, int lane) { for (int o = 1; o < 64; o <<= 1) { float tv = __shfl_up(v, o); if (lane >= o) v += tv; } return v; }
; DI float scan_max(float v, int lane) { for (int o = 1; o < 64; o <<= 1) { float tv = __shfl_up(v, o); if (lane >= o) v = fmaxf(v, tv); } return v; }
; DI void mlstmC_pair(const Params& p, char* lds_all, int pair) {
;     ...
;     const float bc = scan_sum(log_sigmoid(fg), lane);
;     const float as = ig - bc;
;     const float gm = scan_max(as, lane);
;     const float mt = bc + fmaxf(mprev, gm);
;     a_s[lane] = as; c_t[lane] = bc - mt; wint[lane] = expf(bc + mprev - mt); emt[lane] = expf(-mt);
	v_add_f32_e32 v4, v3, v4
	v_cndmask_b32_e64 v3, v4, v3, s[0:1]
	v_add_u32_e32 v4, -2, v27
	v_cmp_lt_i32_e64 s[4:5], v4, v2
	s_nop 1
	v_cndmask_b32_e64 v4, v4, v27, s[4:5]
	v_lshlrev_b32_e32 v4, 2, v4
	ds_bpermute_b32 v5, v4, v3
	v_cmp_gt_u32_e64 s[4:5], 2, v26
	s_waitcnt lgkmcnt(0)
	v_add_f32_e32 v5, v3, v5
	v_cndmask_b32_e64 v3, v5, v3, s[4:5]
	v_add_u32_e32 v5, -4, v27
	v_cmp_lt_i32_e64 s[8:9], v5, v2
	s_nop 1
	v_cndmask_b32_e64 v5, v5, v27, s[8:9]
	v_lshlrev_b32_e32 v5, 2, v5
	ds_bpermute_b32 v6, v5, v3
	v_cmp_gt_u32_e64 s[8:9], 4, v26
	s_waitcnt lgkmcnt(0)
	v_add_f32_e32 v6, v3, v6
	v_cndmask_b32_e64 v3, v6, v3, s[8:9]
	v_add_u32_e32 v6, -8, v27
	v_cmp_lt_i32_e64 s[10:11], v6, v2
	s_nop 1
	v_cndmask_b32_e64 v6, v6, v27, s[10:11]
	v_lshlrev_b32_e32 v6, 2, v6
	ds_bpermute_b32 v7, v6, v3
	v_cmp_gt_u32_e64 s[10:11], 8, v26
	s_waitcnt lgkmcnt(0)
	v_add_f32_e32 v7, v3, v7
	v_cndmask_b32_e64 v3, v7, v3, s[10:11]
	v_add_u32_e32 v7, -16, v27
	v_cmp_lt_i32_e64 s[12:13], v7, v2
	s_nop 1
	v_cndmask_b32_e64 v7, v7, v27, s[12:13]
	v_lshlrev_b32_e32 v7, 2, v7
	ds_bpermute_b32 v8, v7, v3
	v_cmp_gt_u32_e64 s[12:13], 16, v26
	s_waitcnt lgkmcnt(0)
	v_add_f32_e32 v8, v3, v8
	v_cndmask_b32_e64 v3, v8, v3, s[12:13]
	v_subrev_u32_e32 v8, 32, v27
	v_cmp_lt_i32_e64 s[14:15], v8, v2
	s_nop 1
	v_cndmask_b32_e64 v2, v8, v27, s[14:15]
	v_lshlrev_b32_e32 v2, 2, v2
	ds_bpermute_b32 v8, v2, v3
	v_cmp_gt_u32_e64 s[14:15], 32, v26
	s_waitcnt lgkmcnt(0)
	v_add_f32_e32 v8, v3, v8
	v_cndmask_b32_e64 v3, v8, v3, s[14:15]
	v_sub_f32_e32 v0, v0, v3
	ds_bpermute_b32 v1, v1, v0
	s_waitcnt lgkmcnt(0)
	v_max_f32_e32 v1, v1, v1
	v_max_f32_e32 v1, v0, v1
	v_cndmask_b32_e64 v1, v1, v0, s[0:1]
	ds_bpermute_b32 v4, v4, v1
	s_mov_b32 s0, 0x3fb8aa3b
	s_waitcnt lgkmcnt(0)
	v_max_f32_e32 v4, v4, v4
	v_max_f32_e32 v4, v1, v4
	v_cndmask_b32_e64 v1, v4, v1, s[4:5]
	ds_bpermute_b32 v4, v5, v1
	s_waitcnt lgkmcnt(0)
	v_max_f32_e32 v4, v4, v4
	v_max_f32_e32 v4, v1, v4
	v_cndmask_b32_e64 v1, v4, v1, s[8:9]
	ds_bpermute_b32 v4, v6, v1
	s_waitcnt lgkmcnt(0)
	v_max_f32_e32 v4, v4, v4
	v_max_f32_e32 v4, v1, v4
	v_cndmask_b32_e64 v1, v4, v1, s[10:11]
	ds_bpermute_b32 v4, v7, v1
	s_waitcnt lgkmcnt(0)
	v_max_f32_e32 v4, v4, v4
	v_max_f32_e32 v4, v1, v4
	v_cndmask_b32_e64 v1, v4, v1, s[12:13]
	ds_bpermute_b32 v2, v2, v1
	v_max_f32_e32 v4, v1, v1
	s_waitcnt lgkmcnt(0)
	v_max_f32_e32 v2, v2, v2
	v_max_f32_e32 v2, v4, v2
	v_cndmask_b32_e64 v1, v2, v1, s[14:15]
	v_max_f32_e32 v1, v1, v1
	v_max_f32_e32 v2, v43, v43
	v_max_f32_e32 v1, v2, v1
	v_add_f32_e32 v1, v3, v1
	v_lshl_add_u32 v2, v26, 2, v51
	v_sub_f32_e32 v4, v3, v1
	ds_write2st64_b32 v2, v0, v4 offset0:244 offset1:245
	v_add_f32_e32 v0, v43, v3
	v_sub_f32_e32 v0, v0, v1
	v_mul_f32_e32 v3, 0x3fb8aa3b, v0
	v_fma_f32 v4, v0, s0, -v3
	v_rndne_f32_e32 v5, v3
	v_fmac_f32_e32 v4, 0x32a5705f, v0
	v_sub_f32_e32 v3, v3, v5
	v_add_f32_e32 v3, v3, v4
	v_exp_f32_e32 v3, v3
	v_cvt_i32_f32_e32 v4, v5
	s_mov_b32 s0, 0xc2ce8ed0
	v_cmp_ngt_f32_e64 s[0:1], s0, v0
	v_ldexp_f32 v3, v3, v4
	s_nop 0
	v_cndmask_b32_e64 v3, 0, v3, s[0:1]
	s_mov_b32 s0, 0x42b17218
	v_cmp_nlt_f32_e64 s[0:1], s0, v0
	s_nop 1
	v_cndmask_b32_e64 v0, v50, v3, s[0:1]
	v_mul_f32_e32 v3, 0xbfb8aa3b, v1
	v_fma_f32 v4, v1, s19, -v3
	v_rndne_f32_e32 v5, v3
	v_fmac_f32_e32 v4, 0xb2a5705f, v1
	v_sub_f32_e32 v3, v3, v5
	v_add_f32_e32 v3, v3, v4
	v_exp_f32_e32 v3, v3
	v_cvt_i32_f32_e32 v4, v5
	v_cmp_nlt_f32_e64 s[0:1], s20, v1
	v_ldexp_f32 v3, v3, v4
	s_nop 0
	v_cndmask_b32_e64 v3, 0, v3, s[0:1]
	v_cmp_ngt_f32_e64 s[0:1], s21, v1
	s_nop 1
	v_cndmask_b32_e64 v1, v50, v3, s[0:1]
	ds_write2st64_b32 v2, v0, v1 offset0:246 offset1:247
